# N12 + corrected lgkmcnt counts after step loop 3 + 16 cycles of issue slack in front of step loop 1 (robustness; no functional change)
# speedup vs baseline: 1.0014x; 1.0014x over previous
.LBB0_415:
	s_nop 7
	s_nop 7
	v_swap_b32 v17, v12
	v_swap_b32 v19, v14
	s_waitcnt lgkmcnt(0)
	v_pk_mul_f32 v[132:133], v[16:17], v[32:33] op_sel_hi:[1,0]
	v_pk_fma_f32 v[132:133], v[12:13], v[32:33], v[132:133] op_sel:[0,1,0]
	v_pk_fma_f32 v[132:133], v[18:19], v[34:35], v[132:133] op_sel_hi:[1,0,1]
	v_pk_fma_f32 v[132:133], v[14:15], v[34:35], v[132:133] op_sel:[0,1,0]
	ds_read_b128 v[94:97], v42 offset:12288
	ds_read_b128 v[116:119], v42 offset:16384
	ds_read_b128 v[120:123], v42 offset:8192
	ds_read_b128 v[124:127], v42
	ds_read_b64 v[130:131], v92
	v_pk_fma_f32 v[16:17], v[28:29], v[90:91], v[16:17] op_sel_hi:[0,1,1]
	v_pk_fma_f32 v[12:13], v[28:29], v[90:91], v[12:13] op_sel:[1,0,0]
	v_add_f32_dpp v132, v132, v132 quad_perm:[1,0,3,2] row_mask:0xf bank_mask:0xf bound_ctrl:1
	v_add_f32_dpp v133, v133, v133 quad_perm:[1,0,3,2] row_mask:0xf bank_mask:0xf bound_ctrl:1
	v_pk_fma_f32 v[18:19], v[30:31], v[90:91], v[18:19] op_sel_hi:[0,1,1]
	v_add_f32_dpp v132, v132, v132 quad_perm:[2,3,0,1] row_mask:0xf bank_mask:0xf bound_ctrl:1
	v_add_f32_dpp v133, v133, v133 quad_perm:[2,3,0,1] row_mask:0xf bank_mask:0xf bound_ctrl:1
	v_pk_fma_f32 v[14:15], v[30:31], v[90:91], v[14:15] op_sel:[1,0,0]
	v_add_f32_dpp v132, v132, v132 row_half_mirror row_mask:0xf bank_mask:0xf bound_ctrl:1
	v_add_f32_dpp v133, v133, v133 row_half_mirror row_mask:0xf bank_mask:0xf bound_ctrl:1
	ds_read_b64 v[90:91], v115 offset:20736
	v_add_f32_dpp v132, v132, v132 row_mirror row_mask:0xf bank_mask:0xf bound_ctrl:1
	v_add_f32_dpp v133, v133, v133 row_mirror row_mask:0xf bank_mask:0xf bound_ctrl:1
	v_pk_fma_f32 v[16:17], v[24:25], v[132:133], v[16:17] op_sel_hi:[0,1,1]
	v_pk_fma_f32 v[12:13], v[24:25], v[132:133], v[12:13] op_sel:[1,0,0]
	v_pk_fma_f32 v[18:19], v[26:27], v[132:133], v[18:19] op_sel_hi:[0,1,1]
	v_pk_fma_f32 v[14:15], v[26:27], v[132:133], v[14:15] op_sel:[1,0,0]
	s_waitcnt lgkmcnt(1)
	v_pk_mul_f32 v[132:133], v[16:17], v[94:95] op_sel_hi:[1,0]
	v_pk_mul_f32 v[24:25], v[16:17], v[20:21] op_sel_hi:[1,0]
	v_pk_fma_f32 v[132:133], v[12:13], v[94:95], v[132:133] op_sel:[0,1,0]
	v_pk_fma_f32 v[24:25], v[12:13], v[20:21], v[24:25] op_sel:[0,1,0]
	v_pk_fma_f32 v[132:133], v[18:19], v[96:97], v[132:133] op_sel_hi:[1,0,1]
	v_pk_fma_f32 v[24:25], v[18:19], v[22:23], v[24:25] op_sel_hi:[1,0,1]
	v_pk_fma_f32 v[132:133], v[14:15], v[96:97], v[132:133] op_sel:[0,1,0]
	v_pk_fma_f32 v[24:25], v[14:15], v[22:23], v[24:25] op_sel:[0,1,0]
	v_cvt_pk_f16_f32 v96, v24, v25
	v_add_f32_dpp v132, v132, v132 quad_perm:[1,0,3,2] row_mask:0xf bank_mask:0xf bound_ctrl:1
	v_add_f32_dpp v133, v133, v133 quad_perm:[1,0,3,2] row_mask:0xf bank_mask:0xf bound_ctrl:1
	ds_read_b128 v[32:35], v114 offset:12800
	ds_read_b128 v[24:27], v114 offset:16896
	ds_read_b128 v[28:31], v114 offset:8704
	ds_read_b128 v[20:23], v114 offset:512
	v_pk_fma_f32 v[16:17], v[120:121], v[130:131], v[16:17] op_sel_hi:[0,1,1]
	v_add_f32_dpp v132, v132, v132 quad_perm:[2,3,0,1] row_mask:0xf bank_mask:0xf bound_ctrl:1
	v_add_f32_dpp v133, v133, v133 quad_perm:[2,3,0,1] row_mask:0xf bank_mask:0xf bound_ctrl:1
	v_pk_fma_f32 v[12:13], v[120:121], v[130:131], v[12:13] op_sel:[1,0,0]
	v_add_f32_dpp v132, v132, v132 row_half_mirror row_mask:0xf bank_mask:0xf bound_ctrl:1
	v_add_f32_dpp v133, v133, v133 row_half_mirror row_mask:0xf bank_mask:0xf bound_ctrl:1
	v_pk_fma_f32 v[18:19], v[122:123], v[130:131], v[18:19] op_sel_hi:[0,1,1]
	v_pk_fma_f32 v[14:15], v[122:123], v[130:131], v[14:15] op_sel:[1,0,0]
	v_add_f32_dpp v132, v132, v132 row_mirror row_mask:0xf bank_mask:0xf bound_ctrl:1
	v_add_f32_dpp v133, v133, v133 row_mirror row_mask:0xf bank_mask:0xf bound_ctrl:1
	v_pk_fma_f32 v[16:17], v[116:117], v[132:133], v[16:17] op_sel_hi:[0,1,1]
	v_pk_fma_f32 v[12:13], v[116:117], v[132:133], v[12:13] op_sel:[1,0,0]
	v_pk_fma_f32 v[18:19], v[118:119], v[132:133], v[18:19] op_sel_hi:[0,1,1]
	v_pk_fma_f32 v[14:15], v[118:119], v[132:133], v[14:15] op_sel:[1,0,0]
	s_waitcnt lgkmcnt(0)
	v_pk_mul_f32 v[132:133], v[16:17], v[32:33] op_sel_hi:[1,0]
	v_pk_mul_f32 v[94:95], v[16:17], v[124:125] op_sel_hi:[1,0]
	v_pk_fma_f32 v[132:133], v[12:13], v[32:33], v[132:133] op_sel:[0,1,0]
	v_pk_fma_f32 v[94:95], v[12:13], v[124:125], v[94:95] op_sel:[0,1,0]
	v_pk_fma_f32 v[132:133], v[18:19], v[34:35], v[132:133] op_sel_hi:[1,0,1]
	v_pk_fma_f32 v[94:95], v[18:19], v[126:127], v[94:95] op_sel_hi:[1,0,1]
	v_pk_fma_f32 v[132:133], v[14:15], v[34:35], v[132:133] op_sel:[0,1,0]
	v_pk_fma_f32 v[94:95], v[14:15], v[126:127], v[94:95] op_sel:[0,1,0]
	v_cvt_pk_f16_f32 v94, v94, v95
	v_add_f32_dpp v132, v132, v132 quad_perm:[1,0,3,2] row_mask:0xf bank_mask:0xf bound_ctrl:1
	v_add_f32_dpp v133, v133, v133 quad_perm:[1,0,3,2] row_mask:0xf bank_mask:0xf bound_ctrl:1
	ds_write2st64_b32 v93, v96, v94 offset0:0 offset1:4
	ds_read_b128 v[94:97], v42 offset:12800
	ds_read_b128 v[116:119], v42 offset:16896
	ds_read_b128 v[120:123], v42 offset:8704
	ds_read_b128 v[124:127], v42 offset:512
	ds_read_b64 v[130:131], v92 offset:256
	v_pk_fma_f32 v[16:17], v[28:29], v[90:91], v[16:17] op_sel_hi:[0,1,1]
	v_add_f32_dpp v132, v132, v132 quad_perm:[2,3,0,1] row_mask:0xf bank_mask:0xf bound_ctrl:1
	v_add_f32_dpp v133, v133, v133 quad_perm:[2,3,0,1] row_mask:0xf bank_mask:0xf bound_ctrl:1
	v_pk_fma_f32 v[12:13], v[28:29], v[90:91], v[12:13] op_sel:[1,0,0]
	v_add_f32_dpp v132, v132, v132 row_half_mirror row_mask:0xf bank_mask:0xf bound_ctrl:1
	v_add_f32_dpp v133, v133, v133 row_half_mirror row_mask:0xf bank_mask:0xf bound_ctrl:1
	v_pk_fma_f32 v[18:19], v[30:31], v[90:91], v[18:19] op_sel_hi:[0,1,1]
	v_pk_fma_f32 v[14:15], v[30:31], v[90:91], v[14:15] op_sel:[1,0,0]
	ds_read_b64 v[90:91], v115 offset:20992
	v_add_f32_dpp v132, v132, v132 row_mirror row_mask:0xf bank_mask:0xf bound_ctrl:1
	v_add_f32_dpp v133, v133, v133 row_mirror row_mask:0xf bank_mask:0xf bound_ctrl:1
	v_pk_fma_f32 v[16:17], v[24:25], v[132:133], v[16:17] op_sel_hi:[0,1,1]
	v_pk_fma_f32 v[12:13], v[24:25], v[132:133], v[12:13] op_sel:[1,0,0]
	v_pk_fma_f32 v[18:19], v[26:27], v[132:133], v[18:19] op_sel_hi:[0,1,1]
	v_pk_fma_f32 v[14:15], v[26:27], v[132:133], v[14:15] op_sel:[1,0,0]
	s_waitcnt lgkmcnt(1)
	v_pk_mul_f32 v[132:133], v[16:17], v[94:95] op_sel_hi:[1,0]
	v_pk_mul_f32 v[24:25], v[16:17], v[20:21] op_sel_hi:[1,0]
	v_pk_fma_f32 v[132:133], v[12:13], v[94:95], v[132:133] op_sel:[0,1,0]
	v_pk_fma_f32 v[24:25], v[12:13], v[20:21], v[24:25] op_sel:[0,1,0]
	v_pk_fma_f32 v[132:133], v[18:19], v[96:97], v[132:133] op_sel_hi:[1,0,1]
	v_pk_fma_f32 v[24:25], v[18:19], v[22:23], v[24:25] op_sel_hi:[1,0,1]
	v_pk_fma_f32 v[132:133], v[14:15], v[96:97], v[132:133] op_sel:[0,1,0]
	v_pk_fma_f32 v[24:25], v[14:15], v[22:23], v[24:25] op_sel:[0,1,0]
	v_cvt_pk_f16_f32 v96, v24, v25
	v_add_f32_dpp v132, v132, v132 quad_perm:[1,0,3,2] row_mask:0xf bank_mask:0xf bound_ctrl:1
	v_add_f32_dpp v133, v133, v133 quad_perm:[1,0,3,2] row_mask:0xf bank_mask:0xf bound_ctrl:1
	ds_read_b128 v[32:35], v114 offset:13312
	ds_read_b128 v[24:27], v114 offset:17408
	ds_read_b128 v[28:31], v114 offset:9216
	ds_read_b128 v[20:23], v114 offset:1024
	v_pk_fma_f32 v[16:17], v[120:121], v[130:131], v[16:17] op_sel_hi:[0,1,1]
	v_add_f32_dpp v132, v132, v132 quad_perm:[2,3,0,1] row_mask:0xf bank_mask:0xf bound_ctrl:1
	v_add_f32_dpp v133, v133, v133 quad_perm:[2,3,0,1] row_mask:0xf bank_mask:0xf bound_ctrl:1
	v_pk_fma_f32 v[12:13], v[120:121], v[130:131], v[12:13] op_sel:[1,0,0]
	v_add_f32_dpp v132, v132, v132 row_half_mirror row_mask:0xf bank_mask:0xf bound_ctrl:1
	v_add_f32_dpp v133, v133, v133 row_half_mirror row_mask:0xf bank_mask:0xf bound_ctrl:1
	v_pk_fma_f32 v[18:19], v[122:123], v[130:131], v[18:19] op_sel_hi:[0,1,1]
	v_pk_fma_f32 v[14:15], v[122:123], v[130:131], v[14:15] op_sel:[1,0,0]
	v_add_f32_dpp v132, v132, v132 row_mirror row_mask:0xf bank_mask:0xf bound_ctrl:1
	v_add_f32_dpp v133, v133, v133 row_mirror row_mask:0xf bank_mask:0xf bound_ctrl:1
	v_pk_fma_f32 v[16:17], v[116:117], v[132:133], v[16:17] op_sel_hi:[0,1,1]
	v_pk_fma_f32 v[12:13], v[116:117], v[132:133], v[12:13] op_sel:[1,0,0]
	v_pk_fma_f32 v[18:19], v[118:119], v[132:133], v[18:19] op_sel_hi:[0,1,1]
	v_pk_fma_f32 v[14:15], v[118:119], v[132:133], v[14:15] op_sel:[1,0,0]
	s_waitcnt lgkmcnt(0)
	v_pk_mul_f32 v[132:133], v[16:17], v[32:33] op_sel_hi:[1,0]
	v_pk_mul_f32 v[94:95], v[16:17], v[124:125] op_sel_hi:[1,0]
	v_pk_fma_f32 v[132:133], v[12:13], v[32:33], v[132:133] op_sel:[0,1,0]
	v_pk_fma_f32 v[94:95], v[12:13], v[124:125], v[94:95] op_sel:[0,1,0]
	v_pk_fma_f32 v[132:133], v[18:19], v[34:35], v[132:133] op_sel_hi:[1,0,1]
	v_pk_fma_f32 v[94:95], v[18:19], v[126:127], v[94:95] op_sel_hi:[1,0,1]
	v_pk_fma_f32 v[132:133], v[14:15], v[34:35], v[132:133] op_sel:[0,1,0]
	v_pk_fma_f32 v[94:95], v[14:15], v[126:127], v[94:95] op_sel:[0,1,0]
	v_cvt_pk_f16_f32 v94, v94, v95
	v_add_f32_dpp v132, v132, v132 quad_perm:[1,0,3,2] row_mask:0xf bank_mask:0xf bound_ctrl:1
	v_add_f32_dpp v133, v133, v133 quad_perm:[1,0,3,2] row_mask:0xf bank_mask:0xf bound_ctrl:1
	ds_write2st64_b32 v93, v96, v94 offset0:8 offset1:12
	ds_read_b128 v[94:97], v42 offset:13312
	ds_read_b128 v[116:119], v42 offset:17408
	ds_read_b128 v[120:123], v42 offset:9216
	ds_read_b128 v[124:127], v42 offset:1024
	ds_read_b64 v[130:131], v92 offset:512
	v_pk_fma_f32 v[16:17], v[28:29], v[90:91], v[16:17] op_sel_hi:[0,1,1]
	v_add_f32_dpp v132, v132, v132 quad_perm:[2,3,0,1] row_mask:0xf bank_mask:0xf bound_ctrl:1
	v_add_f32_dpp v133, v133, v133 quad_perm:[2,3,0,1] row_mask:0xf bank_mask:0xf bound_ctrl:1
	v_pk_fma_f32 v[12:13], v[28:29], v[90:91], v[12:13] op_sel:[1,0,0]
	v_add_f32_dpp v132, v132, v132 row_half_mirror row_mask:0xf bank_mask:0xf bound_ctrl:1
	v_add_f32_dpp v133, v133, v133 row_half_mirror row_mask:0xf bank_mask:0xf bound_ctrl:1
	v_pk_fma_f32 v[18:19], v[30:31], v[90:91], v[18:19] op_sel_hi:[0,1,1]
	v_pk_fma_f32 v[14:15], v[30:31], v[90:91], v[14:15] op_sel:[1,0,0]
	ds_read_b64 v[90:91], v115 offset:21248
	v_add_f32_dpp v132, v132, v132 row_mirror row_mask:0xf bank_mask:0xf bound_ctrl:1
	v_add_f32_dpp v133, v133, v133 row_mirror row_mask:0xf bank_mask:0xf bound_ctrl:1
	v_pk_fma_f32 v[16:17], v[24:25], v[132:133], v[16:17] op_sel_hi:[0,1,1]
	v_pk_fma_f32 v[12:13], v[24:25], v[132:133], v[12:13] op_sel:[1,0,0]
	v_pk_fma_f32 v[18:19], v[26:27], v[132:133], v[18:19] op_sel_hi:[0,1,1]
	v_pk_fma_f32 v[14:15], v[26:27], v[132:133], v[14:15] op_sel:[1,0,0]
	s_waitcnt lgkmcnt(1)
	v_pk_mul_f32 v[132:133], v[16:17], v[94:95] op_sel_hi:[1,0]
	v_pk_mul_f32 v[24:25], v[16:17], v[20:21] op_sel_hi:[1,0]
	v_pk_fma_f32 v[132:133], v[12:13], v[94:95], v[132:133] op_sel:[0,1,0]
	v_pk_fma_f32 v[24:25], v[12:13], v[20:21], v[24:25] op_sel:[0,1,0]
	v_pk_fma_f32 v[132:133], v[18:19], v[96:97], v[132:133] op_sel_hi:[1,0,1]
	v_pk_fma_f32 v[24:25], v[18:19], v[22:23], v[24:25] op_sel_hi:[1,0,1]
	v_pk_fma_f32 v[132:133], v[14:15], v[96:97], v[132:133] op_sel:[0,1,0]
	v_pk_fma_f32 v[24:25], v[14:15], v[22:23], v[24:25] op_sel:[0,1,0]
	v_cvt_pk_f16_f32 v96, v24, v25
	v_add_f32_dpp v132, v132, v132 quad_perm:[1,0,3,2] row_mask:0xf bank_mask:0xf bound_ctrl:1
	v_add_f32_dpp v133, v133, v133 quad_perm:[1,0,3,2] row_mask:0xf bank_mask:0xf bound_ctrl:1
	ds_read_b128 v[32:35], v114 offset:13824
	ds_read_b128 v[24:27], v114 offset:17920
	ds_read_b128 v[28:31], v114 offset:9728
	ds_read_b128 v[20:23], v114 offset:1536
	v_pk_fma_f32 v[16:17], v[120:121], v[130:131], v[16:17] op_sel_hi:[0,1,1]
	v_add_f32_dpp v132, v132, v132 quad_perm:[2,3,0,1] row_mask:0xf bank_mask:0xf bound_ctrl:1
	v_add_f32_dpp v133, v133, v133 quad_perm:[2,3,0,1] row_mask:0xf bank_mask:0xf bound_ctrl:1
	v_pk_fma_f32 v[12:13], v[120:121], v[130:131], v[12:13] op_sel:[1,0,0]
	v_add_f32_dpp v132, v132, v132 row_half_mirror row_mask:0xf bank_mask:0xf bound_ctrl:1
	v_add_f32_dpp v133, v133, v133 row_half_mirror row_mask:0xf bank_mask:0xf bound_ctrl:1
	v_pk_fma_f32 v[18:19], v[122:123], v[130:131], v[18:19] op_sel_hi:[0,1,1]
	v_pk_fma_f32 v[14:15], v[122:123], v[130:131], v[14:15] op_sel:[1,0,0]
	v_add_f32_dpp v132, v132, v132 row_mirror row_mask:0xf bank_mask:0xf bound_ctrl:1
	v_add_f32_dpp v133, v133, v133 row_mirror row_mask:0xf bank_mask:0xf bound_ctrl:1
	v_pk_fma_f32 v[16:17], v[116:117], v[132:133], v[16:17] op_sel_hi:[0,1,1]
	v_pk_fma_f32 v[12:13], v[116:117], v[132:133], v[12:13] op_sel:[1,0,0]
	v_pk_fma_f32 v[18:19], v[118:119], v[132:133], v[18:19] op_sel_hi:[0,1,1]
	v_pk_fma_f32 v[14:15], v[118:119], v[132:133], v[14:15] op_sel:[1,0,0]
	s_waitcnt lgkmcnt(0)
	v_pk_mul_f32 v[132:133], v[16:17], v[32:33] op_sel_hi:[1,0]
	v_pk_mul_f32 v[94:95], v[16:17], v[124:125] op_sel_hi:[1,0]
	v_pk_fma_f32 v[132:133], v[12:13], v[32:33], v[132:133] op_sel:[0,1,0]
	v_pk_fma_f32 v[94:95], v[12:13], v[124:125], v[94:95] op_sel:[0,1,0]
	v_pk_fma_f32 v[132:133], v[18:19], v[34:35], v[132:133] op_sel_hi:[1,0,1]
	v_pk_fma_f32 v[94:95], v[18:19], v[126:127], v[94:95] op_sel_hi:[1,0,1]
	v_pk_fma_f32 v[132:133], v[14:15], v[34:35], v[132:133] op_sel:[0,1,0]
	v_pk_fma_f32 v[94:95], v[14:15], v[126:127], v[94:95] op_sel:[0,1,0]
	v_cvt_pk_f16_f32 v94, v94, v95
	v_add_f32_dpp v132, v132, v132 quad_perm:[1,0,3,2] row_mask:0xf bank_mask:0xf bound_ctrl:1
	v_add_f32_dpp v133, v133, v133 quad_perm:[1,0,3,2] row_mask:0xf bank_mask:0xf bound_ctrl:1
	ds_write2st64_b32 v93, v96, v94 offset0:16 offset1:20
	ds_read_b128 v[94:97], v42 offset:13824
	ds_read_b128 v[116:119], v42 offset:17920
	ds_read_b128 v[120:123], v42 offset:9728
	ds_read_b128 v[124:127], v42 offset:1536
	ds_read_b64 v[130:131], v92 offset:768
	v_pk_fma_f32 v[16:17], v[28:29], v[90:91], v[16:17] op_sel_hi:[0,1,1]
	v_add_f32_dpp v132, v132, v132 quad_perm:[2,3,0,1] row_mask:0xf bank_mask:0xf bound_ctrl:1
	v_add_f32_dpp v133, v133, v133 quad_perm:[2,3,0,1] row_mask:0xf bank_mask:0xf bound_ctrl:1
	v_pk_fma_f32 v[12:13], v[28:29], v[90:91], v[12:13] op_sel:[1,0,0]
	v_add_f32_dpp v132, v132, v132 row_half_mirror row_mask:0xf bank_mask:0xf bound_ctrl:1
	v_add_f32_dpp v133, v133, v133 row_half_mirror row_mask:0xf bank_mask:0xf bound_ctrl:1
	v_pk_fma_f32 v[18:19], v[30:31], v[90:91], v[18:19] op_sel_hi:[0,1,1]
	v_pk_fma_f32 v[14:15], v[30:31], v[90:91], v[14:15] op_sel:[1,0,0]
	ds_read_b64 v[90:91], v115 offset:21504
	v_add_f32_dpp v132, v132, v132 row_mirror row_mask:0xf bank_mask:0xf bound_ctrl:1
	v_add_f32_dpp v133, v133, v133 row_mirror row_mask:0xf bank_mask:0xf bound_ctrl:1
	v_pk_fma_f32 v[16:17], v[24:25], v[132:133], v[16:17] op_sel_hi:[0,1,1]
	v_pk_fma_f32 v[12:13], v[24:25], v[132:133], v[12:13] op_sel:[1,0,0]
	v_pk_fma_f32 v[18:19], v[26:27], v[132:133], v[18:19] op_sel_hi:[0,1,1]
	v_pk_fma_f32 v[14:15], v[26:27], v[132:133], v[14:15] op_sel:[1,0,0]
	s_waitcnt lgkmcnt(1)
	v_pk_mul_f32 v[132:133], v[16:17], v[94:95] op_sel_hi:[1,0]
	v_pk_mul_f32 v[24:25], v[16:17], v[20:21] op_sel_hi:[1,0]
	v_pk_fma_f32 v[132:133], v[12:13], v[94:95], v[132:133] op_sel:[0,1,0]
	v_pk_fma_f32 v[24:25], v[12:13], v[20:21], v[24:25] op_sel:[0,1,0]
	v_pk_fma_f32 v[132:133], v[18:19], v[96:97], v[132:133] op_sel_hi:[1,0,1]
	v_pk_fma_f32 v[24:25], v[18:19], v[22:23], v[24:25] op_sel_hi:[1,0,1]
	v_pk_fma_f32 v[132:133], v[14:15], v[96:97], v[132:133] op_sel:[0,1,0]
	v_pk_fma_f32 v[24:25], v[14:15], v[22:23], v[24:25] op_sel:[0,1,0]
	v_cvt_pk_f16_f32 v96, v24, v25
	v_add_f32_dpp v132, v132, v132 quad_perm:[1,0,3,2] row_mask:0xf bank_mask:0xf bound_ctrl:1
	v_add_f32_dpp v133, v133, v133 quad_perm:[1,0,3,2] row_mask:0xf bank_mask:0xf bound_ctrl:1
	ds_read_b128 v[32:35], v114 offset:14336
	ds_read_b128 v[24:27], v114 offset:18432
	ds_read_b128 v[28:31], v114 offset:10240
	ds_read_b128 v[20:23], v114 offset:2048
	v_pk_fma_f32 v[16:17], v[120:121], v[130:131], v[16:17] op_sel_hi:[0,1,1]
	v_add_f32_dpp v132, v132, v132 quad_perm:[2,3,0,1] row_mask:0xf bank_mask:0xf bound_ctrl:1
	v_add_f32_dpp v133, v133, v133 quad_perm:[2,3,0,1] row_mask:0xf bank_mask:0xf bound_ctrl:1
	v_pk_fma_f32 v[12:13], v[120:121], v[130:131], v[12:13] op_sel:[1,0,0]
	v_add_f32_dpp v132, v132, v132 row_half_mirror row_mask:0xf bank_mask:0xf bound_ctrl:1
	v_add_f32_dpp v133, v133, v133 row_half_mirror row_mask:0xf bank_mask:0xf bound_ctrl:1
	v_pk_fma_f32 v[18:19], v[122:123], v[130:131], v[18:19] op_sel_hi:[0,1,1]
	v_pk_fma_f32 v[14:15], v[122:123], v[130:131], v[14:15] op_sel:[1,0,0]
	v_add_f32_dpp v132, v132, v132 row_mirror row_mask:0xf bank_mask:0xf bound_ctrl:1
	v_add_f32_dpp v133, v133, v133 row_mirror row_mask:0xf bank_mask:0xf bound_ctrl:1
	v_pk_fma_f32 v[16:17], v[116:117], v[132:133], v[16:17] op_sel_hi:[0,1,1]
	v_pk_fma_f32 v[12:13], v[116:117], v[132:133], v[12:13] op_sel:[1,0,0]
	v_pk_fma_f32 v[18:19], v[118:119], v[132:133], v[18:19] op_sel_hi:[0,1,1]
	v_pk_fma_f32 v[14:15], v[118:119], v[132:133], v[14:15] op_sel:[1,0,0]
	s_waitcnt lgkmcnt(0)
	v_pk_mul_f32 v[132:133], v[16:17], v[32:33] op_sel_hi:[1,0]
	v_pk_mul_f32 v[94:95], v[16:17], v[124:125] op_sel_hi:[1,0]
	v_pk_fma_f32 v[132:133], v[12:13], v[32:33], v[132:133] op_sel:[0,1,0]
	v_pk_fma_f32 v[94:95], v[12:13], v[124:125], v[94:95] op_sel:[0,1,0]
	v_pk_fma_f32 v[132:133], v[18:19], v[34:35], v[132:133] op_sel_hi:[1,0,1]
	v_pk_fma_f32 v[94:95], v[18:19], v[126:127], v[94:95] op_sel_hi:[1,0,1]
	v_pk_fma_f32 v[132:133], v[14:15], v[34:35], v[132:133] op_sel:[0,1,0]
	v_pk_fma_f32 v[94:95], v[14:15], v[126:127], v[94:95] op_sel:[0,1,0]
	v_cvt_pk_f16_f32 v94, v94, v95
	v_add_f32_dpp v132, v132, v132 quad_perm:[1,0,3,2] row_mask:0xf bank_mask:0xf bound_ctrl:1
	v_add_f32_dpp v133, v133, v133 quad_perm:[1,0,3,2] row_mask:0xf bank_mask:0xf bound_ctrl:1
	ds_write2st64_b32 v93, v96, v94 offset0:24 offset1:28
	ds_read_b128 v[94:97], v42 offset:14336
	ds_read_b128 v[116:119], v42 offset:18432
	ds_read_b128 v[120:123], v42 offset:10240
	ds_read_b128 v[124:127], v42 offset:2048
	ds_read_b64 v[130:131], v92 offset:1024
	v_pk_fma_f32 v[16:17], v[28:29], v[90:91], v[16:17] op_sel_hi:[0,1,1]
	v_add_f32_dpp v132, v132, v132 quad_perm:[2,3,0,1] row_mask:0xf bank_mask:0xf bound_ctrl:1
	v_add_f32_dpp v133, v133, v133 quad_perm:[2,3,0,1] row_mask:0xf bank_mask:0xf bound_ctrl:1
	v_pk_fma_f32 v[12:13], v[28:29], v[90:91], v[12:13] op_sel:[1,0,0]
	v_add_f32_dpp v132, v132, v132 row_half_mirror row_mask:0xf bank_mask:0xf bound_ctrl:1
	v_add_f32_dpp v133, v133, v133 row_half_mirror row_mask:0xf bank_mask:0xf bound_ctrl:1
	v_pk_fma_f32 v[18:19], v[30:31], v[90:91], v[18:19] op_sel_hi:[0,1,1]
	v_pk_fma_f32 v[14:15], v[30:31], v[90:91], v[14:15] op_sel:[1,0,0]
	ds_read_b64 v[90:91], v115 offset:21760
	v_add_f32_dpp v132, v132, v132 row_mirror row_mask:0xf bank_mask:0xf bound_ctrl:1
	v_add_f32_dpp v133, v133, v133 row_mirror row_mask:0xf bank_mask:0xf bound_ctrl:1
	v_pk_fma_f32 v[16:17], v[24:25], v[132:133], v[16:17] op_sel_hi:[0,1,1]
	v_pk_fma_f32 v[12:13], v[24:25], v[132:133], v[12:13] op_sel:[1,0,0]
	v_pk_fma_f32 v[18:19], v[26:27], v[132:133], v[18:19] op_sel_hi:[0,1,1]
	v_pk_fma_f32 v[14:15], v[26:27], v[132:133], v[14:15] op_sel:[1,0,0]
	s_waitcnt lgkmcnt(1)
	v_pk_mul_f32 v[132:133], v[16:17], v[94:95] op_sel_hi:[1,0]
	v_pk_mul_f32 v[24:25], v[16:17], v[20:21] op_sel_hi:[1,0]
	v_pk_fma_f32 v[132:133], v[12:13], v[94:95], v[132:133] op_sel:[0,1,0]
	v_pk_fma_f32 v[24:25], v[12:13], v[20:21], v[24:25] op_sel:[0,1,0]
	v_pk_fma_f32 v[132:133], v[18:19], v[96:97], v[132:133] op_sel_hi:[1,0,1]
	v_pk_fma_f32 v[24:25], v[18:19], v[22:23], v[24:25] op_sel_hi:[1,0,1]
	v_pk_fma_f32 v[132:133], v[14:15], v[96:97], v[132:133] op_sel:[0,1,0]
	v_pk_fma_f32 v[24:25], v[14:15], v[22:23], v[24:25] op_sel:[0,1,0]
	v_cvt_pk_f16_f32 v96, v24, v25
	v_add_f32_dpp v132, v132, v132 quad_perm:[1,0,3,2] row_mask:0xf bank_mask:0xf bound_ctrl:1
	v_add_f32_dpp v133, v133, v133 quad_perm:[1,0,3,2] row_mask:0xf bank_mask:0xf bound_ctrl:1
	ds_read_b128 v[32:35], v114 offset:14848
	ds_read_b128 v[24:27], v114 offset:18944
	ds_read_b128 v[28:31], v114 offset:10752
	ds_read_b128 v[20:23], v114 offset:2560
	v_pk_fma_f32 v[16:17], v[120:121], v[130:131], v[16:17] op_sel_hi:[0,1,1]
	v_add_f32_dpp v132, v132, v132 quad_perm:[2,3,0,1] row_mask:0xf bank_mask:0xf bound_ctrl:1
	v_add_f32_dpp v133, v133, v133 quad_perm:[2,3,0,1] row_mask:0xf bank_mask:0xf bound_ctrl:1
	v_pk_fma_f32 v[12:13], v[120:121], v[130:131], v[12:13] op_sel:[1,0,0]
	v_add_f32_dpp v132, v132, v132 row_half_mirror row_mask:0xf bank_mask:0xf bound_ctrl:1
	v_add_f32_dpp v133, v133, v133 row_half_mirror row_mask:0xf bank_mask:0xf bound_ctrl:1
	v_pk_fma_f32 v[18:19], v[122:123], v[130:131], v[18:19] op_sel_hi:[0,1,1]
	v_pk_fma_f32 v[14:15], v[122:123], v[130:131], v[14:15] op_sel:[1,0,0]
	v_add_f32_dpp v132, v132, v132 row_mirror row_mask:0xf bank_mask:0xf bound_ctrl:1
	v_add_f32_dpp v133, v133, v133 row_mirror row_mask:0xf bank_mask:0xf bound_ctrl:1
	v_pk_fma_f32 v[16:17], v[116:117], v[132:133], v[16:17] op_sel_hi:[0,1,1]
	v_pk_fma_f32 v[12:13], v[116:117], v[132:133], v[12:13] op_sel:[1,0,0]
	v_pk_fma_f32 v[18:19], v[118:119], v[132:133], v[18:19] op_sel_hi:[0,1,1]
	v_pk_fma_f32 v[14:15], v[118:119], v[132:133], v[14:15] op_sel:[1,0,0]
	s_waitcnt lgkmcnt(0)
	v_pk_mul_f32 v[132:133], v[16:17], v[32:33] op_sel_hi:[1,0]
	v_pk_mul_f32 v[94:95], v[16:17], v[124:125] op_sel_hi:[1,0]
	v_pk_fma_f32 v[132:133], v[12:13], v[32:33], v[132:133] op_sel:[0,1,0]
	v_pk_fma_f32 v[94:95], v[12:13], v[124:125], v[94:95] op_sel:[0,1,0]
	v_pk_fma_f32 v[132:133], v[18:19], v[34:35], v[132:133] op_sel_hi:[1,0,1]
	v_pk_fma_f32 v[94:95], v[18:19], v[126:127], v[94:95] op_sel_hi:[1,0,1]
	v_pk_fma_f32 v[132:133], v[14:15], v[34:35], v[132:133] op_sel:[0,1,0]
	v_pk_fma_f32 v[94:95], v[14:15], v[126:127], v[94:95] op_sel:[0,1,0]
	v_cvt_pk_f16_f32 v94, v94, v95
	v_add_f32_dpp v132, v132, v132 quad_perm:[1,0,3,2] row_mask:0xf bank_mask:0xf bound_ctrl:1
	v_add_f32_dpp v133, v133, v133 quad_perm:[1,0,3,2] row_mask:0xf bank_mask:0xf bound_ctrl:1
	ds_write2st64_b32 v93, v96, v94 offset0:32 offset1:36
	ds_read_b128 v[94:97], v42 offset:14848
	ds_read_b128 v[116:119], v42 offset:18944
	ds_read_b128 v[120:123], v42 offset:10752
	ds_read_b128 v[124:127], v42 offset:2560
	ds_read_b64 v[130:131], v92 offset:1280
	v_pk_fma_f32 v[16:17], v[28:29], v[90:91], v[16:17] op_sel_hi:[0,1,1]
	v_add_f32_dpp v132, v132, v132 quad_perm:[2,3,0,1] row_mask:0xf bank_mask:0xf bound_ctrl:1
	v_add_f32_dpp v133, v133, v133 quad_perm:[2,3,0,1] row_mask:0xf bank_mask:0xf bound_ctrl:1
	v_pk_fma_f32 v[12:13], v[28:29], v[90:91], v[12:13] op_sel:[1,0,0]
	v_add_f32_dpp v132, v132, v132 row_half_mirror row_mask:0xf bank_mask:0xf bound_ctrl:1
	v_add_f32_dpp v133, v133, v133 row_half_mirror row_mask:0xf bank_mask:0xf bound_ctrl:1
	v_pk_fma_f32 v[18:19], v[30:31], v[90:91], v[18:19] op_sel_hi:[0,1,1]
	v_pk_fma_f32 v[14:15], v[30:31], v[90:91], v[14:15] op_sel:[1,0,0]
	ds_read_b64 v[90:91], v115 offset:22016
	v_add_f32_dpp v132, v132, v132 row_mirror row_mask:0xf bank_mask:0xf bound_ctrl:1
	v_add_f32_dpp v133, v133, v133 row_mirror row_mask:0xf bank_mask:0xf bound_ctrl:1
	v_pk_fma_f32 v[16:17], v[24:25], v[132:133], v[16:17] op_sel_hi:[0,1,1]
	v_pk_fma_f32 v[12:13], v[24:25], v[132:133], v[12:13] op_sel:[1,0,0]
	v_pk_fma_f32 v[18:19], v[26:27], v[132:133], v[18:19] op_sel_hi:[0,1,1]
	v_pk_fma_f32 v[14:15], v[26:27], v[132:133], v[14:15] op_sel:[1,0,0]
	s_waitcnt lgkmcnt(1)
	v_pk_mul_f32 v[132:133], v[16:17], v[94:95] op_sel_hi:[1,0]
	v_pk_mul_f32 v[24:25], v[16:17], v[20:21] op_sel_hi:[1,0]
	v_pk_fma_f32 v[132:133], v[12:13], v[94:95], v[132:133] op_sel:[0,1,0]
	v_pk_fma_f32 v[24:25], v[12:13], v[20:21], v[24:25] op_sel:[0,1,0]
	v_pk_fma_f32 v[132:133], v[18:19], v[96:97], v[132:133] op_sel_hi:[1,0,1]
	v_pk_fma_f32 v[24:25], v[18:19], v[22:23], v[24:25] op_sel_hi:[1,0,1]
	v_pk_fma_f32 v[132:133], v[14:15], v[96:97], v[132:133] op_sel:[0,1,0]
	v_pk_fma_f32 v[24:25], v[14:15], v[22:23], v[24:25] op_sel:[0,1,0]
	v_cvt_pk_f16_f32 v96, v24, v25
	v_add_f32_dpp v132, v132, v132 quad_perm:[1,0,3,2] row_mask:0xf bank_mask:0xf bound_ctrl:1
	v_add_f32_dpp v133, v133, v133 quad_perm:[1,0,3,2] row_mask:0xf bank_mask:0xf bound_ctrl:1
	ds_read_b128 v[32:35], v114 offset:15360
	ds_read_b128 v[24:27], v114 offset:19456
	ds_read_b128 v[28:31], v114 offset:11264
	ds_read_b128 v[20:23], v114 offset:3072
	v_pk_fma_f32 v[16:17], v[120:121], v[130:131], v[16:17] op_sel_hi:[0,1,1]
	v_add_f32_dpp v132, v132, v132 quad_perm:[2,3,0,1] row_mask:0xf bank_mask:0xf bound_ctrl:1
	v_add_f32_dpp v133, v133, v133 quad_perm:[2,3,0,1] row_mask:0xf bank_mask:0xf bound_ctrl:1
	v_pk_fma_f32 v[12:13], v[120:121], v[130:131], v[12:13] op_sel:[1,0,0]
	v_add_f32_dpp v132, v132, v132 row_half_mirror row_mask:0xf bank_mask:0xf bound_ctrl:1
	v_add_f32_dpp v133, v133, v133 row_half_mirror row_mask:0xf bank_mask:0xf bound_ctrl:1
	v_pk_fma_f32 v[18:19], v[122:123], v[130:131], v[18:19] op_sel_hi:[0,1,1]
	v_pk_fma_f32 v[14:15], v[122:123], v[130:131], v[14:15] op_sel:[1,0,0]
	v_add_f32_dpp v132, v132, v132 row_mirror row_mask:0xf bank_mask:0xf bound_ctrl:1
	v_add_f32_dpp v133, v133, v133 row_mirror row_mask:0xf bank_mask:0xf bound_ctrl:1
	v_pk_fma_f32 v[16:17], v[116:117], v[132:133], v[16:17] op_sel_hi:[0,1,1]
	v_pk_fma_f32 v[12:13], v[116:117], v[132:133], v[12:13] op_sel:[1,0,0]
	v_pk_fma_f32 v[18:19], v[118:119], v[132:133], v[18:19] op_sel_hi:[0,1,1]
	v_pk_fma_f32 v[14:15], v[118:119], v[132:133], v[14:15] op_sel:[1,0,0]
	s_waitcnt lgkmcnt(0)
	v_pk_mul_f32 v[132:133], v[16:17], v[32:33] op_sel_hi:[1,0]
	v_pk_mul_f32 v[94:95], v[16:17], v[124:125] op_sel_hi:[1,0]
	v_pk_fma_f32 v[132:133], v[12:13], v[32:33], v[132:133] op_sel:[0,1,0]
	v_pk_fma_f32 v[94:95], v[12:13], v[124:125], v[94:95] op_sel:[0,1,0]
	v_pk_fma_f32 v[132:133], v[18:19], v[34:35], v[132:133] op_sel_hi:[1,0,1]
	v_pk_fma_f32 v[94:95], v[18:19], v[126:127], v[94:95] op_sel_hi:[1,0,1]
	v_pk_fma_f32 v[132:133], v[14:15], v[34:35], v[132:133] op_sel:[0,1,0]
	v_pk_fma_f32 v[94:95], v[14:15], v[126:127], v[94:95] op_sel:[0,1,0]
	v_cvt_pk_f16_f32 v94, v94, v95
	v_add_f32_dpp v132, v132, v132 quad_perm:[1,0,3,2] row_mask:0xf bank_mask:0xf bound_ctrl:1
	v_add_f32_dpp v133, v133, v133 quad_perm:[1,0,3,2] row_mask:0xf bank_mask:0xf bound_ctrl:1
	ds_write2st64_b32 v93, v96, v94 offset0:40 offset1:44
	ds_read_b128 v[94:97], v42 offset:15360
	ds_read_b128 v[116:119], v42 offset:19456
	ds_read_b128 v[120:123], v42 offset:11264
	ds_read_b128 v[124:127], v42 offset:3072
	ds_read_b64 v[130:131], v92 offset:1536
	v_pk_fma_f32 v[16:17], v[28:29], v[90:91], v[16:17] op_sel_hi:[0,1,1]
	v_add_f32_dpp v132, v132, v132 quad_perm:[2,3,0,1] row_mask:0xf bank_mask:0xf bound_ctrl:1
	v_add_f32_dpp v133, v133, v133 quad_perm:[2,3,0,1] row_mask:0xf bank_mask:0xf bound_ctrl:1
	v_pk_fma_f32 v[12:13], v[28:29], v[90:91], v[12:13] op_sel:[1,0,0]
	v_add_f32_dpp v132, v132, v132 row_half_mirror row_mask:0xf bank_mask:0xf bound_ctrl:1
	v_add_f32_dpp v133, v133, v133 row_half_mirror row_mask:0xf bank_mask:0xf bound_ctrl:1
	v_pk_fma_f32 v[18:19], v[30:31], v[90:91], v[18:19] op_sel_hi:[0,1,1]
	v_pk_fma_f32 v[14:15], v[30:31], v[90:91], v[14:15] op_sel:[1,0,0]
	ds_read_b64 v[90:91], v115 offset:22272
	v_add_f32_dpp v132, v132, v132 row_mirror row_mask:0xf bank_mask:0xf bound_ctrl:1
	v_add_f32_dpp v133, v133, v133 row_mirror row_mask:0xf bank_mask:0xf bound_ctrl:1
	v_pk_fma_f32 v[16:17], v[24:25], v[132:133], v[16:17] op_sel_hi:[0,1,1]
	v_pk_fma_f32 v[12:13], v[24:25], v[132:133], v[12:13] op_sel:[1,0,0]
	v_pk_fma_f32 v[18:19], v[26:27], v[132:133], v[18:19] op_sel_hi:[0,1,1]
	v_pk_fma_f32 v[14:15], v[26:27], v[132:133], v[14:15] op_sel:[1,0,0]
	s_waitcnt lgkmcnt(1)
	v_pk_mul_f32 v[132:133], v[16:17], v[94:95] op_sel_hi:[1,0]
	v_pk_mul_f32 v[24:25], v[16:17], v[20:21] op_sel_hi:[1,0]
	v_pk_fma_f32 v[132:133], v[12:13], v[94:95], v[132:133] op_sel:[0,1,0]
	v_pk_fma_f32 v[24:25], v[12:13], v[20:21], v[24:25] op_sel:[0,1,0]
	v_pk_fma_f32 v[132:133], v[18:19], v[96:97], v[132:133] op_sel_hi:[1,0,1]
	v_pk_fma_f32 v[24:25], v[18:19], v[22:23], v[24:25] op_sel_hi:[1,0,1]
	v_pk_fma_f32 v[132:133], v[14:15], v[96:97], v[132:133] op_sel:[0,1,0]
	v_pk_fma_f32 v[24:25], v[14:15], v[22:23], v[24:25] op_sel:[0,1,0]
	v_cvt_pk_f16_f32 v96, v24, v25
	v_add_f32_dpp v132, v132, v132 quad_perm:[1,0,3,2] row_mask:0xf bank_mask:0xf bound_ctrl:1
	v_add_f32_dpp v133, v133, v133 quad_perm:[1,0,3,2] row_mask:0xf bank_mask:0xf bound_ctrl:1
	ds_read_b128 v[32:35], v114 offset:15872
	ds_read_b128 v[24:27], v114 offset:19968
	ds_read_b128 v[28:31], v114 offset:11776
	ds_read_b128 v[20:23], v114 offset:3584
	v_pk_fma_f32 v[16:17], v[120:121], v[130:131], v[16:17] op_sel_hi:[0,1,1]
	v_add_f32_dpp v132, v132, v132 quad_perm:[2,3,0,1] row_mask:0xf bank_mask:0xf bound_ctrl:1
	v_add_f32_dpp v133, v133, v133 quad_perm:[2,3,0,1] row_mask:0xf bank_mask:0xf bound_ctrl:1
	v_pk_fma_f32 v[12:13], v[120:121], v[130:131], v[12:13] op_sel:[1,0,0]
	v_add_f32_dpp v132, v132, v132 row_half_mirror row_mask:0xf bank_mask:0xf bound_ctrl:1
	v_add_f32_dpp v133, v133, v133 row_half_mirror row_mask:0xf bank_mask:0xf bound_ctrl:1
	v_pk_fma_f32 v[18:19], v[122:123], v[130:131], v[18:19] op_sel_hi:[0,1,1]
	v_pk_fma_f32 v[14:15], v[122:123], v[130:131], v[14:15] op_sel:[1,0,0]
	v_add_f32_dpp v132, v132, v132 row_mirror row_mask:0xf bank_mask:0xf bound_ctrl:1
	v_add_f32_dpp v133, v133, v133 row_mirror row_mask:0xf bank_mask:0xf bound_ctrl:1
	v_pk_fma_f32 v[16:17], v[116:117], v[132:133], v[16:17] op_sel_hi:[0,1,1]
	v_pk_fma_f32 v[12:13], v[116:117], v[132:133], v[12:13] op_sel:[1,0,0]
	v_pk_fma_f32 v[18:19], v[118:119], v[132:133], v[18:19] op_sel_hi:[0,1,1]
	v_pk_fma_f32 v[14:15], v[118:119], v[132:133], v[14:15] op_sel:[1,0,0]
	s_waitcnt lgkmcnt(0)
	v_pk_mul_f32 v[132:133], v[16:17], v[32:33] op_sel_hi:[1,0]
	v_pk_mul_f32 v[94:95], v[16:17], v[124:125] op_sel_hi:[1,0]
	v_pk_fma_f32 v[132:133], v[12:13], v[32:33], v[132:133] op_sel:[0,1,0]
	v_pk_fma_f32 v[94:95], v[12:13], v[124:125], v[94:95] op_sel:[0,1,0]
	v_pk_fma_f32 v[132:133], v[18:19], v[34:35], v[132:133] op_sel_hi:[1,0,1]
	v_pk_fma_f32 v[94:95], v[18:19], v[126:127], v[94:95] op_sel_hi:[1,0,1]
	v_pk_fma_f32 v[132:133], v[14:15], v[34:35], v[132:133] op_sel:[0,1,0]
	v_pk_fma_f32 v[94:95], v[14:15], v[126:127], v[94:95] op_sel:[0,1,0]
	v_cvt_pk_f16_f32 v94, v94, v95
	v_add_f32_dpp v132, v132, v132 quad_perm:[1,0,3,2] row_mask:0xf bank_mask:0xf bound_ctrl:1
	v_add_f32_dpp v133, v133, v133 quad_perm:[1,0,3,2] row_mask:0xf bank_mask:0xf bound_ctrl:1
	ds_write2st64_b32 v93, v96, v94 offset0:48 offset1:52
	ds_read_b128 v[94:97], v42 offset:15872
	ds_read_b128 v[116:119], v42 offset:19968
	ds_read_b128 v[120:123], v42 offset:11776
	ds_read_b128 v[124:127], v42 offset:3584
	ds_read_b64 v[130:131], v92 offset:1792
	v_pk_fma_f32 v[16:17], v[28:29], v[90:91], v[16:17] op_sel_hi:[0,1,1]
	v_add_f32_dpp v132, v132, v132 quad_perm:[2,3,0,1] row_mask:0xf bank_mask:0xf bound_ctrl:1
	v_add_f32_dpp v133, v133, v133 quad_perm:[2,3,0,1] row_mask:0xf bank_mask:0xf bound_ctrl:1
	v_pk_fma_f32 v[12:13], v[28:29], v[90:91], v[12:13] op_sel:[1,0,0]
	v_add_f32_dpp v132, v132, v132 row_half_mirror row_mask:0xf bank_mask:0xf bound_ctrl:1
	v_add_f32_dpp v133, v133, v133 row_half_mirror row_mask:0xf bank_mask:0xf bound_ctrl:1
	v_pk_fma_f32 v[18:19], v[30:31], v[90:91], v[18:19] op_sel_hi:[0,1,1]
	v_pk_fma_f32 v[14:15], v[30:31], v[90:91], v[14:15] op_sel:[1,0,0]
	ds_read_b64 v[90:91], v115 offset:22272
	v_add_f32_dpp v132, v132, v132 row_mirror row_mask:0xf bank_mask:0xf bound_ctrl:1
	v_add_f32_dpp v133, v133, v133 row_mirror row_mask:0xf bank_mask:0xf bound_ctrl:1
	v_pk_fma_f32 v[16:17], v[24:25], v[132:133], v[16:17] op_sel_hi:[0,1,1]
	v_pk_fma_f32 v[12:13], v[24:25], v[132:133], v[12:13] op_sel:[1,0,0]
	v_pk_fma_f32 v[18:19], v[26:27], v[132:133], v[18:19] op_sel_hi:[0,1,1]
	v_pk_fma_f32 v[14:15], v[26:27], v[132:133], v[14:15] op_sel:[1,0,0]
	s_waitcnt lgkmcnt(1)
	v_pk_mul_f32 v[132:133], v[16:17], v[94:95] op_sel_hi:[1,0]
	v_pk_mul_f32 v[24:25], v[16:17], v[20:21] op_sel_hi:[1,0]
	v_pk_fma_f32 v[132:133], v[12:13], v[94:95], v[132:133] op_sel:[0,1,0]
	v_pk_fma_f32 v[24:25], v[12:13], v[20:21], v[24:25] op_sel:[0,1,0]
	v_pk_fma_f32 v[132:133], v[18:19], v[96:97], v[132:133] op_sel_hi:[1,0,1]
	v_pk_fma_f32 v[24:25], v[18:19], v[22:23], v[24:25] op_sel_hi:[1,0,1]
	v_pk_fma_f32 v[132:133], v[14:15], v[96:97], v[132:133] op_sel:[0,1,0]
	v_pk_fma_f32 v[24:25], v[14:15], v[22:23], v[24:25] op_sel:[0,1,0]
	v_cvt_pk_f16_f32 v96, v24, v25
	v_add_f32_dpp v132, v132, v132 quad_perm:[1,0,3,2] row_mask:0xf bank_mask:0xf bound_ctrl:1
	v_add_f32_dpp v133, v133, v133 quad_perm:[1,0,3,2] row_mask:0xf bank_mask:0xf bound_ctrl:1
	ds_read_b128 v[32:35], v114 offset:15872
	ds_read_b128 v[24:27], v114 offset:19968
	ds_read_b128 v[28:31], v114 offset:11776
	ds_read_b128 v[20:23], v114 offset:3584
	v_pk_fma_f32 v[16:17], v[120:121], v[130:131], v[16:17] op_sel_hi:[0,1,1]
	v_add_f32_dpp v132, v132, v132 quad_perm:[2,3,0,1] row_mask:0xf bank_mask:0xf bound_ctrl:1
	v_add_f32_dpp v133, v133, v133 quad_perm:[2,3,0,1] row_mask:0xf bank_mask:0xf bound_ctrl:1
	v_pk_fma_f32 v[12:13], v[120:121], v[130:131], v[12:13] op_sel:[1,0,0]
	v_add_f32_dpp v132, v132, v132 row_half_mirror row_mask:0xf bank_mask:0xf bound_ctrl:1
	v_add_f32_dpp v133, v133, v133 row_half_mirror row_mask:0xf bank_mask:0xf bound_ctrl:1
	v_pk_fma_f32 v[18:19], v[122:123], v[130:131], v[18:19] op_sel_hi:[0,1,1]
	v_pk_fma_f32 v[14:15], v[122:123], v[130:131], v[14:15] op_sel:[1,0,0]
	v_add_f32_dpp v132, v132, v132 row_mirror row_mask:0xf bank_mask:0xf bound_ctrl:1
	v_add_f32_dpp v133, v133, v133 row_mirror row_mask:0xf bank_mask:0xf bound_ctrl:1
	v_pk_fma_f32 v[16:17], v[116:117], v[132:133], v[16:17] op_sel_hi:[0,1,1]
	v_pk_fma_f32 v[12:13], v[116:117], v[132:133], v[12:13] op_sel:[1,0,0]
	v_pk_fma_f32 v[18:19], v[118:119], v[132:133], v[18:19] op_sel_hi:[0,1,1]
	v_pk_fma_f32 v[14:15], v[118:119], v[132:133], v[14:15] op_sel:[1,0,0]
	v_pk_mul_f32 v[94:95], v[16:17], v[124:125] op_sel_hi:[1,0]
	v_pk_fma_f32 v[94:95], v[12:13], v[124:125], v[94:95] op_sel:[0,1,0]
	v_pk_fma_f32 v[94:95], v[18:19], v[126:127], v[94:95] op_sel_hi:[1,0,1]
	v_pk_fma_f32 v[94:95], v[14:15], v[126:127], v[94:95] op_sel:[0,1,0]
	v_cvt_pk_f16_f32 v94, v94, v95
	ds_write2st64_b32 v93, v96, v94 offset0:56 offset1:60
	v_swap_b32 v17, v12
	v_swap_b32 v19, v14
	s_waitcnt vmcnt(10) lgkmcnt(1)
	v_cvt_f32_f16_sdwa v91, v60 dst_sel:DWORD dst_unused:UNUSED_PAD src0_sel:WORD_1
	v_cvt_f32_f16_e32 v90, v60
	v_cvt_f32_f16_sdwa v93, v61 dst_sel:DWORD dst_unused:UNUSED_PAD src0_sel:WORD_1
	v_cvt_f32_f16_e32 v92, v61
	s_waitcnt vmcnt(7)
	v_cvt_f32_f16_sdwa v25, v68 dst_sel:DWORD dst_unused:UNUSED_PAD src0_sel:WORD_1
	v_cvt_f32_f16_e32 v24, v68
	v_cvt_f32_f16_sdwa v27, v69 dst_sel:DWORD dst_unused:UNUSED_PAD src0_sel:WORD_1
	v_cvt_f32_f16_e32 v26, v69
	v_pk_mul_f32 v[30:31], v[0:1], v[90:91]
	v_pk_mul_f32 v[28:29], v[2:3], v[92:93]
	v_pk_mul_f32 v[96:97], v[30:31], v[30:31]
	v_pk_mul_f32 v[94:95], v[28:29], v[28:29]
	v_add_f32_e32 v42, v96, v97
	v_cvt_f32_f16_sdwa v33, v58 dst_sel:DWORD dst_unused:UNUSED_PAD src0_sel:WORD_1
	v_cvt_f32_f16_e32 v32, v58
	v_cvt_f32_f16_sdwa v35, v59 dst_sel:DWORD dst_unused:UNUSED_PAD src0_sel:WORD_1
	v_cvt_f32_f16_e32 v34, v59
	v_add_f32_e32 v42, v94, v42
	v_add_f32_e32 v42, v95, v42
	v_pk_add_f32 v[94:95], v[24:25], -1.0 op_sel_hi:[1,0]
	v_pk_add_f32 v[96:97], v[26:27], -1.0 op_sel_hi:[1,0]
	v_pk_fma_f32 v[94:95], v[4:5], v[94:95], 1.0 op_sel_hi:[1,1,0]
	v_pk_fma_f32 v[96:97], v[6:7], v[96:97], 1.0 op_sel_hi:[1,1,0]
	v_pk_mul_f32 v[94:95], v[90:91], v[94:95]
	v_pk_mul_f32 v[96:97], v[92:93], v[96:97]
	v_pk_mul_f32 v[90:91], v[32:33], v[94:95]
	v_pk_mul_f32 v[92:93], v[34:35], v[96:97]
	v_pk_mul_f32 v[90:91], v[8:9], v[90:91]
	v_pk_mul_f32 v[92:93], v[10:11], v[92:93]
	v_add_f32_e32 v90, v90, v91
	v_add_f32_e32 v91, v92, v93
	ds_read_b128 v[20:23], v114 offset:7936
	v_add_f32_e32 v90, v90, v91
	v_add_f32_dpp v42, v42, v42 quad_perm:[1,0,3,2] row_mask:0xf bank_mask:0xf bound_ctrl:1
	s_nop 0
	v_add_f32_dpp v90, v90, v90 quad_perm:[1,0,3,2] row_mask:0xf bank_mask:0xf bound_ctrl:1
	v_add_f32_dpp v42, v42, v42 quad_perm:[2,3,0,1] row_mask:0xf bank_mask:0xf bound_ctrl:1
	s_nop 0
	v_add_f32_dpp v90, v90, v90 quad_perm:[2,3,0,1] row_mask:0xf bank_mask:0xf bound_ctrl:1
	v_add_f32_dpp v42, v42, v42 row_half_mirror row_mask:0xf bank_mask:0xf bound_ctrl:1
	s_nop 0
	v_add_f32_dpp v90, v90, v90 row_half_mirror row_mask:0xf bank_mask:0xf bound_ctrl:1
	v_mov_b32_dpp v116, v42 row_mirror row_mask:0xf bank_mask:0xf bound_ctrl:1
	s_nop 0
	v_mov_b32_dpp v91, v90 row_mirror row_mask:0xf bank_mask:0xf bound_ctrl:1
	s_and_saveexec_b64 s[12:13], s[6:7]
	s_cbranch_execz .LBB0_419
	s_add_i32 s50, s94, 16
	v_cmp_lt_u32_e32 vcc, s50, v106
	s_and_b64 exec, exec, vcc
	s_cbranch_execz .LBB0_419
	v_add_f32_e32 v92, v90, v91
	v_add_u32_e32 v90, s50, v46
	v_ashrrev_i32_e32 v91, 31, v90
	v_lshlrev_b64 v[90:91], 6, v[90:91]
	v_lshl_add_u64 v[90:91], s[58:59], 0, v[90:91]
	global_store_dword v[90:91], v92, off

.LBB0_437:
	v_swap_b32 v93, v94
	v_swap_b32 v33, v34
	s_waitcnt lgkmcnt(0)
	v_pk_mul_f32 v[130:131], v[92:93], v[24:25] op_sel_hi:[1,0]
	v_pk_fma_f32 v[130:131], v[94:95], v[24:25], v[130:131] op_sel:[0,1,0]
	v_pk_fma_f32 v[130:131], v[32:33], v[26:27], v[130:131] op_sel_hi:[1,0,1]
	v_pk_fma_f32 v[130:131], v[34:35], v[26:27], v[130:131] op_sel:[0,1,0]
	ds_read_b128 v[12:15], v113 offset:12288
	ds_read_b128 v[116:119], v113 offset:16384
	ds_read_b128 v[120:123], v113 offset:8192
	ds_read_b128 v[124:127], v113
	ds_read_b64 v[90:91], v112
	v_pk_fma_f32 v[92:93], v[28:29], v[96:97], v[92:93] op_sel_hi:[0,1,1]
	v_pk_fma_f32 v[94:95], v[28:29], v[96:97], v[94:95] op_sel:[1,0,0]
	v_add_f32_dpp v130, v130, v130 quad_perm:[1,0,3,2] row_mask:0xf bank_mask:0xf bound_ctrl:1
	v_add_f32_dpp v131, v131, v131 quad_perm:[1,0,3,2] row_mask:0xf bank_mask:0xf bound_ctrl:1
	v_pk_fma_f32 v[32:33], v[30:31], v[96:97], v[32:33] op_sel_hi:[0,1,1]
	v_add_f32_dpp v130, v130, v130 quad_perm:[2,3,0,1] row_mask:0xf bank_mask:0xf bound_ctrl:1
	v_add_f32_dpp v131, v131, v131 quad_perm:[2,3,0,1] row_mask:0xf bank_mask:0xf bound_ctrl:1
	v_pk_fma_f32 v[34:35], v[30:31], v[96:97], v[34:35] op_sel:[1,0,0]
	v_add_f32_dpp v130, v130, v130 row_half_mirror row_mask:0xf bank_mask:0xf bound_ctrl:1
	v_add_f32_dpp v131, v131, v131 row_half_mirror row_mask:0xf bank_mask:0xf bound_ctrl:1
	ds_read_b64 v[96:97], v115 offset:20736
	v_add_f32_dpp v130, v130, v130 row_mirror row_mask:0xf bank_mask:0xf bound_ctrl:1
	v_add_f32_dpp v131, v131, v131 row_mirror row_mask:0xf bank_mask:0xf bound_ctrl:1
	v_pk_fma_f32 v[92:93], v[20:21], v[130:131], v[92:93] op_sel_hi:[0,1,1]
	v_pk_fma_f32 v[94:95], v[20:21], v[130:131], v[94:95] op_sel:[1,0,0]
	v_pk_fma_f32 v[32:33], v[22:23], v[130:131], v[32:33] op_sel_hi:[0,1,1]
	v_pk_fma_f32 v[34:35], v[22:23], v[130:131], v[34:35] op_sel:[1,0,0]
	s_waitcnt lgkmcnt(1)
	v_pk_mul_f32 v[130:131], v[92:93], v[12:13] op_sel_hi:[1,0]
	v_pk_mul_f32 v[20:21], v[92:93], v[16:17] op_sel_hi:[1,0]
	v_pk_fma_f32 v[130:131], v[94:95], v[12:13], v[130:131] op_sel:[0,1,0]
	v_pk_fma_f32 v[20:21], v[94:95], v[16:17], v[20:21] op_sel:[0,1,0]
	v_pk_fma_f32 v[130:131], v[32:33], v[14:15], v[130:131] op_sel_hi:[1,0,1]
	v_pk_fma_f32 v[20:21], v[32:33], v[18:19], v[20:21] op_sel_hi:[1,0,1]
	v_pk_fma_f32 v[130:131], v[34:35], v[14:15], v[130:131] op_sel:[0,1,0]
	v_pk_fma_f32 v[20:21], v[34:35], v[18:19], v[20:21] op_sel:[0,1,0]
	v_cvt_pk_f16_f32 v14, v20, v21
	v_add_f32_dpp v130, v130, v130 quad_perm:[1,0,3,2] row_mask:0xf bank_mask:0xf bound_ctrl:1
	v_add_f32_dpp v131, v131, v131 quad_perm:[1,0,3,2] row_mask:0xf bank_mask:0xf bound_ctrl:1
	ds_read_b128 v[24:27], v114 offset:12800
	ds_read_b128 v[20:23], v114 offset:16896
	ds_read_b128 v[28:31], v114 offset:8704
	ds_read_b128 v[16:19], v114 offset:512
	v_pk_fma_f32 v[92:93], v[120:121], v[90:91], v[92:93] op_sel_hi:[0,1,1]
	v_add_f32_dpp v130, v130, v130 quad_perm:[2,3,0,1] row_mask:0xf bank_mask:0xf bound_ctrl:1
	v_add_f32_dpp v131, v131, v131 quad_perm:[2,3,0,1] row_mask:0xf bank_mask:0xf bound_ctrl:1
	v_pk_fma_f32 v[94:95], v[120:121], v[90:91], v[94:95] op_sel:[1,0,0]
	v_add_f32_dpp v130, v130, v130 row_half_mirror row_mask:0xf bank_mask:0xf bound_ctrl:1
	v_add_f32_dpp v131, v131, v131 row_half_mirror row_mask:0xf bank_mask:0xf bound_ctrl:1
	v_pk_fma_f32 v[32:33], v[122:123], v[90:91], v[32:33] op_sel_hi:[0,1,1]
	v_pk_fma_f32 v[34:35], v[122:123], v[90:91], v[34:35] op_sel:[1,0,0]
	v_add_f32_dpp v130, v130, v130 row_mirror row_mask:0xf bank_mask:0xf bound_ctrl:1
	v_add_f32_dpp v131, v131, v131 row_mirror row_mask:0xf bank_mask:0xf bound_ctrl:1
	v_pk_fma_f32 v[92:93], v[116:117], v[130:131], v[92:93] op_sel_hi:[0,1,1]
	v_pk_fma_f32 v[94:95], v[116:117], v[130:131], v[94:95] op_sel:[1,0,0]
	v_pk_fma_f32 v[32:33], v[118:119], v[130:131], v[32:33] op_sel_hi:[0,1,1]
	v_pk_fma_f32 v[34:35], v[118:119], v[130:131], v[34:35] op_sel:[1,0,0]
	s_waitcnt lgkmcnt(0)
	v_pk_mul_f32 v[130:131], v[92:93], v[24:25] op_sel_hi:[1,0]
	v_pk_mul_f32 v[12:13], v[92:93], v[124:125] op_sel_hi:[1,0]
	v_pk_fma_f32 v[130:131], v[94:95], v[24:25], v[130:131] op_sel:[0,1,0]
	v_pk_fma_f32 v[12:13], v[94:95], v[124:125], v[12:13] op_sel:[0,1,0]
	v_pk_fma_f32 v[130:131], v[32:33], v[26:27], v[130:131] op_sel_hi:[1,0,1]
	v_pk_fma_f32 v[12:13], v[32:33], v[126:127], v[12:13] op_sel_hi:[1,0,1]
	v_pk_fma_f32 v[130:131], v[34:35], v[26:27], v[130:131] op_sel:[0,1,0]
	v_pk_fma_f32 v[12:13], v[34:35], v[126:127], v[12:13] op_sel:[0,1,0]
	v_cvt_pk_f16_f32 v12, v12, v13
	v_add_f32_dpp v130, v130, v130 quad_perm:[1,0,3,2] row_mask:0xf bank_mask:0xf bound_ctrl:1
	v_add_f32_dpp v131, v131, v131 quad_perm:[1,0,3,2] row_mask:0xf bank_mask:0xf bound_ctrl:1
	ds_write2st64_b32 v47, v14, v12 offset0:0 offset1:4
	ds_read_b128 v[12:15], v113 offset:12800
	ds_read_b128 v[116:119], v113 offset:16896
	ds_read_b128 v[120:123], v113 offset:8704
	ds_read_b128 v[124:127], v113 offset:512
	ds_read_b64 v[90:91], v112 offset:256
	v_pk_fma_f32 v[92:93], v[28:29], v[96:97], v[92:93] op_sel_hi:[0,1,1]
	v_add_f32_dpp v130, v130, v130 quad_perm:[2,3,0,1] row_mask:0xf bank_mask:0xf bound_ctrl:1
	v_add_f32_dpp v131, v131, v131 quad_perm:[2,3,0,1] row_mask:0xf bank_mask:0xf bound_ctrl:1
	v_pk_fma_f32 v[94:95], v[28:29], v[96:97], v[94:95] op_sel:[1,0,0]
	v_add_f32_dpp v130, v130, v130 row_half_mirror row_mask:0xf bank_mask:0xf bound_ctrl:1
	v_add_f32_dpp v131, v131, v131 row_half_mirror row_mask:0xf bank_mask:0xf bound_ctrl:1
	v_pk_fma_f32 v[32:33], v[30:31], v[96:97], v[32:33] op_sel_hi:[0,1,1]
	v_pk_fma_f32 v[34:35], v[30:31], v[96:97], v[34:35] op_sel:[1,0,0]
	ds_read_b64 v[96:97], v115 offset:20992
	v_add_f32_dpp v130, v130, v130 row_mirror row_mask:0xf bank_mask:0xf bound_ctrl:1
	v_add_f32_dpp v131, v131, v131 row_mirror row_mask:0xf bank_mask:0xf bound_ctrl:1
	v_pk_fma_f32 v[92:93], v[20:21], v[130:131], v[92:93] op_sel_hi:[0,1,1]
	v_pk_fma_f32 v[94:95], v[20:21], v[130:131], v[94:95] op_sel:[1,0,0]
	v_pk_fma_f32 v[32:33], v[22:23], v[130:131], v[32:33] op_sel_hi:[0,1,1]
	v_pk_fma_f32 v[34:35], v[22:23], v[130:131], v[34:35] op_sel:[1,0,0]
	s_waitcnt lgkmcnt(1)
	v_pk_mul_f32 v[130:131], v[92:93], v[12:13] op_sel_hi:[1,0]
	v_pk_mul_f32 v[20:21], v[92:93], v[16:17] op_sel_hi:[1,0]
	v_pk_fma_f32 v[130:131], v[94:95], v[12:13], v[130:131] op_sel:[0,1,0]
	v_pk_fma_f32 v[20:21], v[94:95], v[16:17], v[20:21] op_sel:[0,1,0]
	v_pk_fma_f32 v[130:131], v[32:33], v[14:15], v[130:131] op_sel_hi:[1,0,1]
	v_pk_fma_f32 v[20:21], v[32:33], v[18:19], v[20:21] op_sel_hi:[1,0,1]
	v_pk_fma_f32 v[130:131], v[34:35], v[14:15], v[130:131] op_sel:[0,1,0]
	v_pk_fma_f32 v[20:21], v[34:35], v[18:19], v[20:21] op_sel:[0,1,0]
	v_cvt_pk_f16_f32 v14, v20, v21
	v_add_f32_dpp v130, v130, v130 quad_perm:[1,0,3,2] row_mask:0xf bank_mask:0xf bound_ctrl:1
	v_add_f32_dpp v131, v131, v131 quad_perm:[1,0,3,2] row_mask:0xf bank_mask:0xf bound_ctrl:1
	ds_read_b128 v[24:27], v114 offset:13312
	ds_read_b128 v[20:23], v114 offset:17408
	ds_read_b128 v[28:31], v114 offset:9216
	ds_read_b128 v[16:19], v114 offset:1024
	v_pk_fma_f32 v[92:93], v[120:121], v[90:91], v[92:93] op_sel_hi:[0,1,1]
	v_add_f32_dpp v130, v130, v130 quad_perm:[2,3,0,1] row_mask:0xf bank_mask:0xf bound_ctrl:1
	v_add_f32_dpp v131, v131, v131 quad_perm:[2,3,0,1] row_mask:0xf bank_mask:0xf bound_ctrl:1
	v_pk_fma_f32 v[94:95], v[120:121], v[90:91], v[94:95] op_sel:[1,0,0]
	v_add_f32_dpp v130, v130, v130 row_half_mirror row_mask:0xf bank_mask:0xf bound_ctrl:1
	v_add_f32_dpp v131, v131, v131 row_half_mirror row_mask:0xf bank_mask:0xf bound_ctrl:1
	v_pk_fma_f32 v[32:33], v[122:123], v[90:91], v[32:33] op_sel_hi:[0,1,1]
	v_pk_fma_f32 v[34:35], v[122:123], v[90:91], v[34:35] op_sel:[1,0,0]
	v_add_f32_dpp v130, v130, v130 row_mirror row_mask:0xf bank_mask:0xf bound_ctrl:1
	v_add_f32_dpp v131, v131, v131 row_mirror row_mask:0xf bank_mask:0xf bound_ctrl:1
	v_pk_fma_f32 v[92:93], v[116:117], v[130:131], v[92:93] op_sel_hi:[0,1,1]
	v_pk_fma_f32 v[94:95], v[116:117], v[130:131], v[94:95] op_sel:[1,0,0]
	v_pk_fma_f32 v[32:33], v[118:119], v[130:131], v[32:33] op_sel_hi:[0,1,1]
	v_pk_fma_f32 v[34:35], v[118:119], v[130:131], v[34:35] op_sel:[1,0,0]
	s_waitcnt lgkmcnt(0)
	v_pk_mul_f32 v[130:131], v[92:93], v[24:25] op_sel_hi:[1,0]
	v_pk_mul_f32 v[12:13], v[92:93], v[124:125] op_sel_hi:[1,0]
	v_pk_fma_f32 v[130:131], v[94:95], v[24:25], v[130:131] op_sel:[0,1,0]
	v_pk_fma_f32 v[12:13], v[94:95], v[124:125], v[12:13] op_sel:[0,1,0]
	v_pk_fma_f32 v[130:131], v[32:33], v[26:27], v[130:131] op_sel_hi:[1,0,1]
	v_pk_fma_f32 v[12:13], v[32:33], v[126:127], v[12:13] op_sel_hi:[1,0,1]
	v_pk_fma_f32 v[130:131], v[34:35], v[26:27], v[130:131] op_sel:[0,1,0]
	v_pk_fma_f32 v[12:13], v[34:35], v[126:127], v[12:13] op_sel:[0,1,0]
	v_cvt_pk_f16_f32 v12, v12, v13
	v_add_f32_dpp v130, v130, v130 quad_perm:[1,0,3,2] row_mask:0xf bank_mask:0xf bound_ctrl:1
	v_add_f32_dpp v131, v131, v131 quad_perm:[1,0,3,2] row_mask:0xf bank_mask:0xf bound_ctrl:1
	ds_write2st64_b32 v47, v14, v12 offset0:8 offset1:12
	ds_read_b128 v[12:15], v113 offset:13312
	ds_read_b128 v[116:119], v113 offset:17408
	ds_read_b128 v[120:123], v113 offset:9216
	ds_read_b128 v[124:127], v113 offset:1024
	ds_read_b64 v[90:91], v112 offset:512
	v_pk_fma_f32 v[92:93], v[28:29], v[96:97], v[92:93] op_sel_hi:[0,1,1]
	v_add_f32_dpp v130, v130, v130 quad_perm:[2,3,0,1] row_mask:0xf bank_mask:0xf bound_ctrl:1
	v_add_f32_dpp v131, v131, v131 quad_perm:[2,3,0,1] row_mask:0xf bank_mask:0xf bound_ctrl:1
	v_pk_fma_f32 v[94:95], v[28:29], v[96:97], v[94:95] op_sel:[1,0,0]
	v_add_f32_dpp v130, v130, v130 row_half_mirror row_mask:0xf bank_mask:0xf bound_ctrl:1
	v_add_f32_dpp v131, v131, v131 row_half_mirror row_mask:0xf bank_mask:0xf bound_ctrl:1
	v_pk_fma_f32 v[32:33], v[30:31], v[96:97], v[32:33] op_sel_hi:[0,1,1]
	v_pk_fma_f32 v[34:35], v[30:31], v[96:97], v[34:35] op_sel:[1,0,0]
	ds_read_b64 v[96:97], v115 offset:21248
	v_add_f32_dpp v130, v130, v130 row_mirror row_mask:0xf bank_mask:0xf bound_ctrl:1
	v_add_f32_dpp v131, v131, v131 row_mirror row_mask:0xf bank_mask:0xf bound_ctrl:1
	v_pk_fma_f32 v[92:93], v[20:21], v[130:131], v[92:93] op_sel_hi:[0,1,1]
	v_pk_fma_f32 v[94:95], v[20:21], v[130:131], v[94:95] op_sel:[1,0,0]
	v_pk_fma_f32 v[32:33], v[22:23], v[130:131], v[32:33] op_sel_hi:[0,1,1]
	v_pk_fma_f32 v[34:35], v[22:23], v[130:131], v[34:35] op_sel:[1,0,0]
	s_waitcnt lgkmcnt(1)
	v_pk_mul_f32 v[130:131], v[92:93], v[12:13] op_sel_hi:[1,0]
	v_pk_mul_f32 v[20:21], v[92:93], v[16:17] op_sel_hi:[1,0]
	v_pk_fma_f32 v[130:131], v[94:95], v[12:13], v[130:131] op_sel:[0,1,0]
	v_pk_fma_f32 v[20:21], v[94:95], v[16:17], v[20:21] op_sel:[0,1,0]
	v_pk_fma_f32 v[130:131], v[32:33], v[14:15], v[130:131] op_sel_hi:[1,0,1]
	v_pk_fma_f32 v[20:21], v[32:33], v[18:19], v[20:21] op_sel_hi:[1,0,1]
	v_pk_fma_f32 v[130:131], v[34:35], v[14:15], v[130:131] op_sel:[0,1,0]
	v_pk_fma_f32 v[20:21], v[34:35], v[18:19], v[20:21] op_sel:[0,1,0]
	v_cvt_pk_f16_f32 v14, v20, v21
	v_add_f32_dpp v130, v130, v130 quad_perm:[1,0,3,2] row_mask:0xf bank_mask:0xf bound_ctrl:1
	v_add_f32_dpp v131, v131, v131 quad_perm:[1,0,3,2] row_mask:0xf bank_mask:0xf bound_ctrl:1
	ds_read_b128 v[24:27], v114 offset:13824
	ds_read_b128 v[20:23], v114 offset:17920
	ds_read_b128 v[28:31], v114 offset:9728
	ds_read_b128 v[16:19], v114 offset:1536
	v_pk_fma_f32 v[92:93], v[120:121], v[90:91], v[92:93] op_sel_hi:[0,1,1]
	v_add_f32_dpp v130, v130, v130 quad_perm:[2,3,0,1] row_mask:0xf bank_mask:0xf bound_ctrl:1
	v_add_f32_dpp v131, v131, v131 quad_perm:[2,3,0,1] row_mask:0xf bank_mask:0xf bound_ctrl:1
	v_pk_fma_f32 v[94:95], v[120:121], v[90:91], v[94:95] op_sel:[1,0,0]
	v_add_f32_dpp v130, v130, v130 row_half_mirror row_mask:0xf bank_mask:0xf bound_ctrl:1
	v_add_f32_dpp v131, v131, v131 row_half_mirror row_mask:0xf bank_mask:0xf bound_ctrl:1
	v_pk_fma_f32 v[32:33], v[122:123], v[90:91], v[32:33] op_sel_hi:[0,1,1]
	v_pk_fma_f32 v[34:35], v[122:123], v[90:91], v[34:35] op_sel:[1,0,0]
	v_add_f32_dpp v130, v130, v130 row_mirror row_mask:0xf bank_mask:0xf bound_ctrl:1
	v_add_f32_dpp v131, v131, v131 row_mirror row_mask:0xf bank_mask:0xf bound_ctrl:1
	v_pk_fma_f32 v[92:93], v[116:117], v[130:131], v[92:93] op_sel_hi:[0,1,1]
	v_pk_fma_f32 v[94:95], v[116:117], v[130:131], v[94:95] op_sel:[1,0,0]
	v_pk_fma_f32 v[32:33], v[118:119], v[130:131], v[32:33] op_sel_hi:[0,1,1]
	v_pk_fma_f32 v[34:35], v[118:119], v[130:131], v[34:35] op_sel:[1,0,0]
	s_waitcnt lgkmcnt(0)
	v_pk_mul_f32 v[130:131], v[92:93], v[24:25] op_sel_hi:[1,0]
	v_pk_mul_f32 v[12:13], v[92:93], v[124:125] op_sel_hi:[1,0]
	v_pk_fma_f32 v[130:131], v[94:95], v[24:25], v[130:131] op_sel:[0,1,0]
	v_pk_fma_f32 v[12:13], v[94:95], v[124:125], v[12:13] op_sel:[0,1,0]
	v_pk_fma_f32 v[130:131], v[32:33], v[26:27], v[130:131] op_sel_hi:[1,0,1]
	v_pk_fma_f32 v[12:13], v[32:33], v[126:127], v[12:13] op_sel_hi:[1,0,1]
	v_pk_fma_f32 v[130:131], v[34:35], v[26:27], v[130:131] op_sel:[0,1,0]
	v_pk_fma_f32 v[12:13], v[34:35], v[126:127], v[12:13] op_sel:[0,1,0]
	v_cvt_pk_f16_f32 v12, v12, v13
	v_add_f32_dpp v130, v130, v130 quad_perm:[1,0,3,2] row_mask:0xf bank_mask:0xf bound_ctrl:1
	v_add_f32_dpp v131, v131, v131 quad_perm:[1,0,3,2] row_mask:0xf bank_mask:0xf bound_ctrl:1
	ds_write2st64_b32 v47, v14, v12 offset0:16 offset1:20
	ds_read_b128 v[12:15], v113 offset:13824
	ds_read_b128 v[116:119], v113 offset:17920
	ds_read_b128 v[120:123], v113 offset:9728
	ds_read_b128 v[124:127], v113 offset:1536
	ds_read_b64 v[90:91], v112 offset:768
	v_pk_fma_f32 v[92:93], v[28:29], v[96:97], v[92:93] op_sel_hi:[0,1,1]
	v_add_f32_dpp v130, v130, v130 quad_perm:[2,3,0,1] row_mask:0xf bank_mask:0xf bound_ctrl:1
	v_add_f32_dpp v131, v131, v131 quad_perm:[2,3,0,1] row_mask:0xf bank_mask:0xf bound_ctrl:1
	v_pk_fma_f32 v[94:95], v[28:29], v[96:97], v[94:95] op_sel:[1,0,0]
	v_add_f32_dpp v130, v130, v130 row_half_mirror row_mask:0xf bank_mask:0xf bound_ctrl:1
	v_add_f32_dpp v131, v131, v131 row_half_mirror row_mask:0xf bank_mask:0xf bound_ctrl:1
	v_pk_fma_f32 v[32:33], v[30:31], v[96:97], v[32:33] op_sel_hi:[0,1,1]
	v_pk_fma_f32 v[34:35], v[30:31], v[96:97], v[34:35] op_sel:[1,0,0]
	ds_read_b64 v[96:97], v115 offset:21504
	v_add_f32_dpp v130, v130, v130 row_mirror row_mask:0xf bank_mask:0xf bound_ctrl:1
	v_add_f32_dpp v131, v131, v131 row_mirror row_mask:0xf bank_mask:0xf bound_ctrl:1
	v_pk_fma_f32 v[92:93], v[20:21], v[130:131], v[92:93] op_sel_hi:[0,1,1]
	v_pk_fma_f32 v[94:95], v[20:21], v[130:131], v[94:95] op_sel:[1,0,0]
	v_pk_fma_f32 v[32:33], v[22:23], v[130:131], v[32:33] op_sel_hi:[0,1,1]
	v_pk_fma_f32 v[34:35], v[22:23], v[130:131], v[34:35] op_sel:[1,0,0]
	s_waitcnt lgkmcnt(1)
	v_pk_mul_f32 v[130:131], v[92:93], v[12:13] op_sel_hi:[1,0]
	v_pk_mul_f32 v[20:21], v[92:93], v[16:17] op_sel_hi:[1,0]
	v_pk_fma_f32 v[130:131], v[94:95], v[12:13], v[130:131] op_sel:[0,1,0]
	v_pk_fma_f32 v[20:21], v[94:95], v[16:17], v[20:21] op_sel:[0,1,0]
	v_pk_fma_f32 v[130:131], v[32:33], v[14:15], v[130:131] op_sel_hi:[1,0,1]
	v_pk_fma_f32 v[20:21], v[32:33], v[18:19], v[20:21] op_sel_hi:[1,0,1]
	v_pk_fma_f32 v[130:131], v[34:35], v[14:15], v[130:131] op_sel:[0,1,0]
	v_pk_fma_f32 v[20:21], v[34:35], v[18:19], v[20:21] op_sel:[0,1,0]
	v_cvt_pk_f16_f32 v14, v20, v21
	v_add_f32_dpp v130, v130, v130 quad_perm:[1,0,3,2] row_mask:0xf bank_mask:0xf bound_ctrl:1
	v_add_f32_dpp v131, v131, v131 quad_perm:[1,0,3,2] row_mask:0xf bank_mask:0xf bound_ctrl:1
	ds_read_b128 v[24:27], v114 offset:14336
	ds_read_b128 v[20:23], v114 offset:18432
	ds_read_b128 v[28:31], v114 offset:10240
	ds_read_b128 v[16:19], v114 offset:2048
	v_pk_fma_f32 v[92:93], v[120:121], v[90:91], v[92:93] op_sel_hi:[0,1,1]
	v_add_f32_dpp v130, v130, v130 quad_perm:[2,3,0,1] row_mask:0xf bank_mask:0xf bound_ctrl:1
	v_add_f32_dpp v131, v131, v131 quad_perm:[2,3,0,1] row_mask:0xf bank_mask:0xf bound_ctrl:1
	v_pk_fma_f32 v[94:95], v[120:121], v[90:91], v[94:95] op_sel:[1,0,0]
	v_add_f32_dpp v130, v130, v130 row_half_mirror row_mask:0xf bank_mask:0xf bound_ctrl:1
	v_add_f32_dpp v131, v131, v131 row_half_mirror row_mask:0xf bank_mask:0xf bound_ctrl:1
	v_pk_fma_f32 v[32:33], v[122:123], v[90:91], v[32:33] op_sel_hi:[0,1,1]
	v_pk_fma_f32 v[34:35], v[122:123], v[90:91], v[34:35] op_sel:[1,0,0]
	v_add_f32_dpp v130, v130, v130 row_mirror row_mask:0xf bank_mask:0xf bound_ctrl:1
	v_add_f32_dpp v131, v131, v131 row_mirror row_mask:0xf bank_mask:0xf bound_ctrl:1
	v_pk_fma_f32 v[92:93], v[116:117], v[130:131], v[92:93] op_sel_hi:[0,1,1]
	v_pk_fma_f32 v[94:95], v[116:117], v[130:131], v[94:95] op_sel:[1,0,0]
	v_pk_fma_f32 v[32:33], v[118:119], v[130:131], v[32:33] op_sel_hi:[0,1,1]
	v_pk_fma_f32 v[34:35], v[118:119], v[130:131], v[34:35] op_sel:[1,0,0]
	s_waitcnt lgkmcnt(0)
	v_pk_mul_f32 v[130:131], v[92:93], v[24:25] op_sel_hi:[1,0]
	v_pk_mul_f32 v[12:13], v[92:93], v[124:125] op_sel_hi:[1,0]
	v_pk_fma_f32 v[130:131], v[94:95], v[24:25], v[130:131] op_sel:[0,1,0]
	v_pk_fma_f32 v[12:13], v[94:95], v[124:125], v[12:13] op_sel:[0,1,0]
	v_pk_fma_f32 v[130:131], v[32:33], v[26:27], v[130:131] op_sel_hi:[1,0,1]
	v_pk_fma_f32 v[12:13], v[32:33], v[126:127], v[12:13] op_sel_hi:[1,0,1]
	v_pk_fma_f32 v[130:131], v[34:35], v[26:27], v[130:131] op_sel:[0,1,0]
	v_pk_fma_f32 v[12:13], v[34:35], v[126:127], v[12:13] op_sel:[0,1,0]
	v_cvt_pk_f16_f32 v12, v12, v13
	v_add_f32_dpp v130, v130, v130 quad_perm:[1,0,3,2] row_mask:0xf bank_mask:0xf bound_ctrl:1
	v_add_f32_dpp v131, v131, v131 quad_perm:[1,0,3,2] row_mask:0xf bank_mask:0xf bound_ctrl:1
	ds_write2st64_b32 v47, v14, v12 offset0:24 offset1:28
	ds_read_b128 v[12:15], v113 offset:14336
	ds_read_b128 v[116:119], v113 offset:18432
	ds_read_b128 v[120:123], v113 offset:10240
	ds_read_b128 v[124:127], v113 offset:2048
	ds_read_b64 v[90:91], v112 offset:1024
	v_pk_fma_f32 v[92:93], v[28:29], v[96:97], v[92:93] op_sel_hi:[0,1,1]
	v_add_f32_dpp v130, v130, v130 quad_perm:[2,3,0,1] row_mask:0xf bank_mask:0xf bound_ctrl:1
	v_add_f32_dpp v131, v131, v131 quad_perm:[2,3,0,1] row_mask:0xf bank_mask:0xf bound_ctrl:1
	v_pk_fma_f32 v[94:95], v[28:29], v[96:97], v[94:95] op_sel:[1,0,0]
	v_add_f32_dpp v130, v130, v130 row_half_mirror row_mask:0xf bank_mask:0xf bound_ctrl:1
	v_add_f32_dpp v131, v131, v131 row_half_mirror row_mask:0xf bank_mask:0xf bound_ctrl:1
	v_pk_fma_f32 v[32:33], v[30:31], v[96:97], v[32:33] op_sel_hi:[0,1,1]
	v_pk_fma_f32 v[34:35], v[30:31], v[96:97], v[34:35] op_sel:[1,0,0]
	ds_read_b64 v[96:97], v115 offset:21760
	v_add_f32_dpp v130, v130, v130 row_mirror row_mask:0xf bank_mask:0xf bound_ctrl:1
	v_add_f32_dpp v131, v131, v131 row_mirror row_mask:0xf bank_mask:0xf bound_ctrl:1
	v_pk_fma_f32 v[92:93], v[20:21], v[130:131], v[92:93] op_sel_hi:[0,1,1]
	v_pk_fma_f32 v[94:95], v[20:21], v[130:131], v[94:95] op_sel:[1,0,0]
	v_pk_fma_f32 v[32:33], v[22:23], v[130:131], v[32:33] op_sel_hi:[0,1,1]
	v_pk_fma_f32 v[34:35], v[22:23], v[130:131], v[34:35] op_sel:[1,0,0]
	s_waitcnt lgkmcnt(1)
	v_pk_mul_f32 v[130:131], v[92:93], v[12:13] op_sel_hi:[1,0]
	v_pk_mul_f32 v[20:21], v[92:93], v[16:17] op_sel_hi:[1,0]
	v_pk_fma_f32 v[130:131], v[94:95], v[12:13], v[130:131] op_sel:[0,1,0]
	v_pk_fma_f32 v[20:21], v[94:95], v[16:17], v[20:21] op_sel:[0,1,0]
	v_pk_fma_f32 v[130:131], v[32:33], v[14:15], v[130:131] op_sel_hi:[1,0,1]
	v_pk_fma_f32 v[20:21], v[32:33], v[18:19], v[20:21] op_sel_hi:[1,0,1]
	v_pk_fma_f32 v[130:131], v[34:35], v[14:15], v[130:131] op_sel:[0,1,0]
	v_pk_fma_f32 v[20:21], v[34:35], v[18:19], v[20:21] op_sel:[0,1,0]
	v_cvt_pk_f16_f32 v14, v20, v21
	v_add_f32_dpp v130, v130, v130 quad_perm:[1,0,3,2] row_mask:0xf bank_mask:0xf bound_ctrl:1
	v_add_f32_dpp v131, v131, v131 quad_perm:[1,0,3,2] row_mask:0xf bank_mask:0xf bound_ctrl:1
	ds_read_b128 v[24:27], v114 offset:14848
	ds_read_b128 v[20:23], v114 offset:18944
	ds_read_b128 v[28:31], v114 offset:10752
	ds_read_b128 v[16:19], v114 offset:2560
	v_pk_fma_f32 v[92:93], v[120:121], v[90:91], v[92:93] op_sel_hi:[0,1,1]
	v_add_f32_dpp v130, v130, v130 quad_perm:[2,3,0,1] row_mask:0xf bank_mask:0xf bound_ctrl:1
	v_add_f32_dpp v131, v131, v131 quad_perm:[2,3,0,1] row_mask:0xf bank_mask:0xf bound_ctrl:1
	v_pk_fma_f32 v[94:95], v[120:121], v[90:91], v[94:95] op_sel:[1,0,0]
	v_add_f32_dpp v130, v130, v130 row_half_mirror row_mask:0xf bank_mask:0xf bound_ctrl:1
	v_add_f32_dpp v131, v131, v131 row_half_mirror row_mask:0xf bank_mask:0xf bound_ctrl:1
	v_pk_fma_f32 v[32:33], v[122:123], v[90:91], v[32:33] op_sel_hi:[0,1,1]
	v_pk_fma_f32 v[34:35], v[122:123], v[90:91], v[34:35] op_sel:[1,0,0]
	v_add_f32_dpp v130, v130, v130 row_mirror row_mask:0xf bank_mask:0xf bound_ctrl:1
	v_add_f32_dpp v131, v131, v131 row_mirror row_mask:0xf bank_mask:0xf bound_ctrl:1
	v_pk_fma_f32 v[92:93], v[116:117], v[130:131], v[92:93] op_sel_hi:[0,1,1]
	v_pk_fma_f32 v[94:95], v[116:117], v[130:131], v[94:95] op_sel:[1,0,0]
	v_pk_fma_f32 v[32:33], v[118:119], v[130:131], v[32:33] op_sel_hi:[0,1,1]
	v_pk_fma_f32 v[34:35], v[118:119], v[130:131], v[34:35] op_sel:[1,0,0]
	s_waitcnt lgkmcnt(0)
	v_pk_mul_f32 v[130:131], v[92:93], v[24:25] op_sel_hi:[1,0]
	v_pk_mul_f32 v[12:13], v[92:93], v[124:125] op_sel_hi:[1,0]
	v_pk_fma_f32 v[130:131], v[94:95], v[24:25], v[130:131] op_sel:[0,1,0]
	v_pk_fma_f32 v[12:13], v[94:95], v[124:125], v[12:13] op_sel:[0,1,0]
	v_pk_fma_f32 v[130:131], v[32:33], v[26:27], v[130:131] op_sel_hi:[1,0,1]
	v_pk_fma_f32 v[12:13], v[32:33], v[126:127], v[12:13] op_sel_hi:[1,0,1]
	v_pk_fma_f32 v[130:131], v[34:35], v[26:27], v[130:131] op_sel:[0,1,0]
	v_pk_fma_f32 v[12:13], v[34:35], v[126:127], v[12:13] op_sel:[0,1,0]
	v_cvt_pk_f16_f32 v12, v12, v13
	v_add_f32_dpp v130, v130, v130 quad_perm:[1,0,3,2] row_mask:0xf bank_mask:0xf bound_ctrl:1
	v_add_f32_dpp v131, v131, v131 quad_perm:[1,0,3,2] row_mask:0xf bank_mask:0xf bound_ctrl:1
	ds_write2st64_b32 v47, v14, v12 offset0:32 offset1:36
	ds_read_b128 v[12:15], v113 offset:14848
	ds_read_b128 v[116:119], v113 offset:18944
	ds_read_b128 v[120:123], v113 offset:10752
	ds_read_b128 v[124:127], v113 offset:2560
	ds_read_b64 v[90:91], v112 offset:1280
	v_pk_fma_f32 v[92:93], v[28:29], v[96:97], v[92:93] op_sel_hi:[0,1,1]
	v_add_f32_dpp v130, v130, v130 quad_perm:[2,3,0,1] row_mask:0xf bank_mask:0xf bound_ctrl:1
	v_add_f32_dpp v131, v131, v131 quad_perm:[2,3,0,1] row_mask:0xf bank_mask:0xf bound_ctrl:1
	v_pk_fma_f32 v[94:95], v[28:29], v[96:97], v[94:95] op_sel:[1,0,0]
	v_add_f32_dpp v130, v130, v130 row_half_mirror row_mask:0xf bank_mask:0xf bound_ctrl:1
	v_add_f32_dpp v131, v131, v131 row_half_mirror row_mask:0xf bank_mask:0xf bound_ctrl:1
	v_pk_fma_f32 v[32:33], v[30:31], v[96:97], v[32:33] op_sel_hi:[0,1,1]
	v_pk_fma_f32 v[34:35], v[30:31], v[96:97], v[34:35] op_sel:[1,0,0]
	ds_read_b64 v[96:97], v115 offset:22016
	v_add_f32_dpp v130, v130, v130 row_mirror row_mask:0xf bank_mask:0xf bound_ctrl:1
	v_add_f32_dpp v131, v131, v131 row_mirror row_mask:0xf bank_mask:0xf bound_ctrl:1
	v_pk_fma_f32 v[92:93], v[20:21], v[130:131], v[92:93] op_sel_hi:[0,1,1]
	v_pk_fma_f32 v[94:95], v[20:21], v[130:131], v[94:95] op_sel:[1,0,0]
	v_pk_fma_f32 v[32:33], v[22:23], v[130:131], v[32:33] op_sel_hi:[0,1,1]
	v_pk_fma_f32 v[34:35], v[22:23], v[130:131], v[34:35] op_sel:[1,0,0]
	s_waitcnt lgkmcnt(1)
	v_pk_mul_f32 v[130:131], v[92:93], v[12:13] op_sel_hi:[1,0]
	v_pk_mul_f32 v[20:21], v[92:93], v[16:17] op_sel_hi:[1,0]
	v_pk_fma_f32 v[130:131], v[94:95], v[12:13], v[130:131] op_sel:[0,1,0]
	v_pk_fma_f32 v[20:21], v[94:95], v[16:17], v[20:21] op_sel:[0,1,0]
	v_pk_fma_f32 v[130:131], v[32:33], v[14:15], v[130:131] op_sel_hi:[1,0,1]
	v_pk_fma_f32 v[20:21], v[32:33], v[18:19], v[20:21] op_sel_hi:[1,0,1]
	v_pk_fma_f32 v[130:131], v[34:35], v[14:15], v[130:131] op_sel:[0,1,0]
	v_pk_fma_f32 v[20:21], v[34:35], v[18:19], v[20:21] op_sel:[0,1,0]
	v_cvt_pk_f16_f32 v14, v20, v21
	v_add_f32_dpp v130, v130, v130 quad_perm:[1,0,3,2] row_mask:0xf bank_mask:0xf bound_ctrl:1
	v_add_f32_dpp v131, v131, v131 quad_perm:[1,0,3,2] row_mask:0xf bank_mask:0xf bound_ctrl:1
	ds_read_b128 v[24:27], v114 offset:15360
	ds_read_b128 v[20:23], v114 offset:19456
	ds_read_b128 v[28:31], v114 offset:11264
	ds_read_b128 v[16:19], v114 offset:3072
	v_pk_fma_f32 v[92:93], v[120:121], v[90:91], v[92:93] op_sel_hi:[0,1,1]
	v_add_f32_dpp v130, v130, v130 quad_perm:[2,3,0,1] row_mask:0xf bank_mask:0xf bound_ctrl:1
	v_add_f32_dpp v131, v131, v131 quad_perm:[2,3,0,1] row_mask:0xf bank_mask:0xf bound_ctrl:1
	v_pk_fma_f32 v[94:95], v[120:121], v[90:91], v[94:95] op_sel:[1,0,0]
	v_add_f32_dpp v130, v130, v130 row_half_mirror row_mask:0xf bank_mask:0xf bound_ctrl:1
	v_add_f32_dpp v131, v131, v131 row_half_mirror row_mask:0xf bank_mask:0xf bound_ctrl:1
	v_pk_fma_f32 v[32:33], v[122:123], v[90:91], v[32:33] op_sel_hi:[0,1,1]
	v_pk_fma_f32 v[34:35], v[122:123], v[90:91], v[34:35] op_sel:[1,0,0]
	v_add_f32_dpp v130, v130, v130 row_mirror row_mask:0xf bank_mask:0xf bound_ctrl:1
	v_add_f32_dpp v131, v131, v131 row_mirror row_mask:0xf bank_mask:0xf bound_ctrl:1
	v_pk_fma_f32 v[92:93], v[116:117], v[130:131], v[92:93] op_sel_hi:[0,1,1]
	v_pk_fma_f32 v[94:95], v[116:117], v[130:131], v[94:95] op_sel:[1,0,0]
	v_pk_fma_f32 v[32:33], v[118:119], v[130:131], v[32:33] op_sel_hi:[0,1,1]
	v_pk_fma_f32 v[34:35], v[118:119], v[130:131], v[34:35] op_sel:[1,0,0]
	s_waitcnt lgkmcnt(0)
	v_pk_mul_f32 v[130:131], v[92:93], v[24:25] op_sel_hi:[1,0]
	v_pk_mul_f32 v[12:13], v[92:93], v[124:125] op_sel_hi:[1,0]
	v_pk_fma_f32 v[130:131], v[94:95], v[24:25], v[130:131] op_sel:[0,1,0]
	v_pk_fma_f32 v[12:13], v[94:95], v[124:125], v[12:13] op_sel:[0,1,0]
	v_pk_fma_f32 v[130:131], v[32:33], v[26:27], v[130:131] op_sel_hi:[1,0,1]
	v_pk_fma_f32 v[12:13], v[32:33], v[126:127], v[12:13] op_sel_hi:[1,0,1]
	v_pk_fma_f32 v[130:131], v[34:35], v[26:27], v[130:131] op_sel:[0,1,0]
	v_pk_fma_f32 v[12:13], v[34:35], v[126:127], v[12:13] op_sel:[0,1,0]
	v_cvt_pk_f16_f32 v12, v12, v13
	v_add_f32_dpp v130, v130, v130 quad_perm:[1,0,3,2] row_mask:0xf bank_mask:0xf bound_ctrl:1
	v_add_f32_dpp v131, v131, v131 quad_perm:[1,0,3,2] row_mask:0xf bank_mask:0xf bound_ctrl:1
	ds_write2st64_b32 v47, v14, v12 offset0:40 offset1:44
	ds_read_b128 v[12:15], v113 offset:15360
	ds_read_b128 v[116:119], v113 offset:19456
	ds_read_b128 v[120:123], v113 offset:11264
	ds_read_b128 v[124:127], v113 offset:3072
	ds_read_b64 v[90:91], v112 offset:1536
	v_pk_fma_f32 v[92:93], v[28:29], v[96:97], v[92:93] op_sel_hi:[0,1,1]
	v_add_f32_dpp v130, v130, v130 quad_perm:[2,3,0,1] row_mask:0xf bank_mask:0xf bound_ctrl:1
	v_add_f32_dpp v131, v131, v131 quad_perm:[2,3,0,1] row_mask:0xf bank_mask:0xf bound_ctrl:1
	v_pk_fma_f32 v[94:95], v[28:29], v[96:97], v[94:95] op_sel:[1,0,0]
	v_add_f32_dpp v130, v130, v130 row_half_mirror row_mask:0xf bank_mask:0xf bound_ctrl:1
	v_add_f32_dpp v131, v131, v131 row_half_mirror row_mask:0xf bank_mask:0xf bound_ctrl:1
	v_pk_fma_f32 v[32:33], v[30:31], v[96:97], v[32:33] op_sel_hi:[0,1,1]
	v_pk_fma_f32 v[34:35], v[30:31], v[96:97], v[34:35] op_sel:[1,0,0]
	ds_read_b64 v[96:97], v115 offset:22272
	v_add_f32_dpp v130, v130, v130 row_mirror row_mask:0xf bank_mask:0xf bound_ctrl:1
	v_add_f32_dpp v131, v131, v131 row_mirror row_mask:0xf bank_mask:0xf bound_ctrl:1
	v_pk_fma_f32 v[92:93], v[20:21], v[130:131], v[92:93] op_sel_hi:[0,1,1]
	v_pk_fma_f32 v[94:95], v[20:21], v[130:131], v[94:95] op_sel:[1,0,0]
	v_pk_fma_f32 v[32:33], v[22:23], v[130:131], v[32:33] op_sel_hi:[0,1,1]
	v_pk_fma_f32 v[34:35], v[22:23], v[130:131], v[34:35] op_sel:[1,0,0]
	s_waitcnt lgkmcnt(1)
	v_pk_mul_f32 v[130:131], v[92:93], v[12:13] op_sel_hi:[1,0]
	v_pk_mul_f32 v[20:21], v[92:93], v[16:17] op_sel_hi:[1,0]
	v_pk_fma_f32 v[130:131], v[94:95], v[12:13], v[130:131] op_sel:[0,1,0]
	v_pk_fma_f32 v[20:21], v[94:95], v[16:17], v[20:21] op_sel:[0,1,0]
	v_pk_fma_f32 v[130:131], v[32:33], v[14:15], v[130:131] op_sel_hi:[1,0,1]
	v_pk_fma_f32 v[20:21], v[32:33], v[18:19], v[20:21] op_sel_hi:[1,0,1]
	v_pk_fma_f32 v[130:131], v[34:35], v[14:15], v[130:131] op_sel:[0,1,0]
	v_pk_fma_f32 v[20:21], v[34:35], v[18:19], v[20:21] op_sel:[0,1,0]
	v_cvt_pk_f16_f32 v14, v20, v21
	v_add_f32_dpp v130, v130, v130 quad_perm:[1,0,3,2] row_mask:0xf bank_mask:0xf bound_ctrl:1
	v_add_f32_dpp v131, v131, v131 quad_perm:[1,0,3,2] row_mask:0xf bank_mask:0xf bound_ctrl:1
	ds_read_b128 v[24:27], v114 offset:15872
	ds_read_b128 v[20:23], v114 offset:19968
	ds_read_b128 v[28:31], v114 offset:11776
	ds_read_b128 v[16:19], v114 offset:3584
	v_pk_fma_f32 v[92:93], v[120:121], v[90:91], v[92:93] op_sel_hi:[0,1,1]
	v_add_f32_dpp v130, v130, v130 quad_perm:[2,3,0,1] row_mask:0xf bank_mask:0xf bound_ctrl:1
	v_add_f32_dpp v131, v131, v131 quad_perm:[2,3,0,1] row_mask:0xf bank_mask:0xf bound_ctrl:1
	v_pk_fma_f32 v[94:95], v[120:121], v[90:91], v[94:95] op_sel:[1,0,0]
	v_add_f32_dpp v130, v130, v130 row_half_mirror row_mask:0xf bank_mask:0xf bound_ctrl:1
	v_add_f32_dpp v131, v131, v131 row_half_mirror row_mask:0xf bank_mask:0xf bound_ctrl:1
	v_pk_fma_f32 v[32:33], v[122:123], v[90:91], v[32:33] op_sel_hi:[0,1,1]
	v_pk_fma_f32 v[34:35], v[122:123], v[90:91], v[34:35] op_sel:[1,0,0]
	v_add_f32_dpp v130, v130, v130 row_mirror row_mask:0xf bank_mask:0xf bound_ctrl:1
	v_add_f32_dpp v131, v131, v131 row_mirror row_mask:0xf bank_mask:0xf bound_ctrl:1
	v_pk_fma_f32 v[92:93], v[116:117], v[130:131], v[92:93] op_sel_hi:[0,1,1]
	v_pk_fma_f32 v[94:95], v[116:117], v[130:131], v[94:95] op_sel:[1,0,0]
	v_pk_fma_f32 v[32:33], v[118:119], v[130:131], v[32:33] op_sel_hi:[0,1,1]
	v_pk_fma_f32 v[34:35], v[118:119], v[130:131], v[34:35] op_sel:[1,0,0]
	s_waitcnt lgkmcnt(0)
	v_pk_mul_f32 v[130:131], v[92:93], v[24:25] op_sel_hi:[1,0]
	v_pk_mul_f32 v[12:13], v[92:93], v[124:125] op_sel_hi:[1,0]
	v_pk_fma_f32 v[130:131], v[94:95], v[24:25], v[130:131] op_sel:[0,1,0]
	v_pk_fma_f32 v[12:13], v[94:95], v[124:125], v[12:13] op_sel:[0,1,0]
	v_pk_fma_f32 v[130:131], v[32:33], v[26:27], v[130:131] op_sel_hi:[1,0,1]
	v_pk_fma_f32 v[12:13], v[32:33], v[126:127], v[12:13] op_sel_hi:[1,0,1]
	v_pk_fma_f32 v[130:131], v[34:35], v[26:27], v[130:131] op_sel:[0,1,0]
	v_pk_fma_f32 v[12:13], v[34:35], v[126:127], v[12:13] op_sel:[0,1,0]
	v_cvt_pk_f16_f32 v12, v12, v13
	v_add_f32_dpp v130, v130, v130 quad_perm:[1,0,3,2] row_mask:0xf bank_mask:0xf bound_ctrl:1
	v_add_f32_dpp v131, v131, v131 quad_perm:[1,0,3,2] row_mask:0xf bank_mask:0xf bound_ctrl:1
	ds_write2st64_b32 v47, v14, v12 offset0:48 offset1:52
	ds_read_b128 v[12:15], v113 offset:15872
	ds_read_b128 v[116:119], v113 offset:19968
	ds_read_b128 v[120:123], v113 offset:11776
	ds_read_b128 v[124:127], v113 offset:3584
	ds_read_b64 v[90:91], v112 offset:1792
	v_pk_fma_f32 v[92:93], v[28:29], v[96:97], v[92:93] op_sel_hi:[0,1,1]
	v_add_f32_dpp v130, v130, v130 quad_perm:[2,3,0,1] row_mask:0xf bank_mask:0xf bound_ctrl:1
	v_add_f32_dpp v131, v131, v131 quad_perm:[2,3,0,1] row_mask:0xf bank_mask:0xf bound_ctrl:1
	v_pk_fma_f32 v[94:95], v[28:29], v[96:97], v[94:95] op_sel:[1,0,0]
	v_add_f32_dpp v130, v130, v130 row_half_mirror row_mask:0xf bank_mask:0xf bound_ctrl:1
	v_add_f32_dpp v131, v131, v131 row_half_mirror row_mask:0xf bank_mask:0xf bound_ctrl:1
	v_pk_fma_f32 v[32:33], v[30:31], v[96:97], v[32:33] op_sel_hi:[0,1,1]
	v_pk_fma_f32 v[34:35], v[30:31], v[96:97], v[34:35] op_sel:[1,0,0]
	ds_read_b64 v[96:97], v115 offset:22272
	v_add_f32_dpp v130, v130, v130 row_mirror row_mask:0xf bank_mask:0xf bound_ctrl:1
	v_add_f32_dpp v131, v131, v131 row_mirror row_mask:0xf bank_mask:0xf bound_ctrl:1
	v_pk_fma_f32 v[92:93], v[20:21], v[130:131], v[92:93] op_sel_hi:[0,1,1]
	v_pk_fma_f32 v[94:95], v[20:21], v[130:131], v[94:95] op_sel:[1,0,0]
	v_pk_fma_f32 v[32:33], v[22:23], v[130:131], v[32:33] op_sel_hi:[0,1,1]
	v_pk_fma_f32 v[34:35], v[22:23], v[130:131], v[34:35] op_sel:[1,0,0]
	s_waitcnt lgkmcnt(1)
	v_pk_mul_f32 v[130:131], v[92:93], v[12:13] op_sel_hi:[1,0]
	v_pk_mul_f32 v[20:21], v[92:93], v[16:17] op_sel_hi:[1,0]
	v_pk_fma_f32 v[130:131], v[94:95], v[12:13], v[130:131] op_sel:[0,1,0]
	v_pk_fma_f32 v[20:21], v[94:95], v[16:17], v[20:21] op_sel:[0,1,0]
	v_pk_fma_f32 v[130:131], v[32:33], v[14:15], v[130:131] op_sel_hi:[1,0,1]
	v_pk_fma_f32 v[20:21], v[32:33], v[18:19], v[20:21] op_sel_hi:[1,0,1]
	v_pk_fma_f32 v[130:131], v[34:35], v[14:15], v[130:131] op_sel:[0,1,0]
	v_pk_fma_f32 v[20:21], v[34:35], v[18:19], v[20:21] op_sel:[0,1,0]
	v_cvt_pk_f16_f32 v14, v20, v21
	v_add_f32_dpp v130, v130, v130 quad_perm:[1,0,3,2] row_mask:0xf bank_mask:0xf bound_ctrl:1
	v_add_f32_dpp v131, v131, v131 quad_perm:[1,0,3,2] row_mask:0xf bank_mask:0xf bound_ctrl:1
	ds_read_b128 v[24:27], v114 offset:15872
	ds_read_b128 v[20:23], v114 offset:19968
	ds_read_b128 v[28:31], v114 offset:11776
	ds_read_b128 v[16:19], v114 offset:3584
	v_pk_fma_f32 v[92:93], v[120:121], v[90:91], v[92:93] op_sel_hi:[0,1,1]
	v_add_f32_dpp v130, v130, v130 quad_perm:[2,3,0,1] row_mask:0xf bank_mask:0xf bound_ctrl:1
	v_add_f32_dpp v131, v131, v131 quad_perm:[2,3,0,1] row_mask:0xf bank_mask:0xf bound_ctrl:1
	v_pk_fma_f32 v[94:95], v[120:121], v[90:91], v[94:95] op_sel:[1,0,0]
	v_add_f32_dpp v130, v130, v130 row_half_mirror row_mask:0xf bank_mask:0xf bound_ctrl:1
	v_add_f32_dpp v131, v131, v131 row_half_mirror row_mask:0xf bank_mask:0xf bound_ctrl:1
	v_pk_fma_f32 v[32:33], v[122:123], v[90:91], v[32:33] op_sel_hi:[0,1,1]
	v_pk_fma_f32 v[34:35], v[122:123], v[90:91], v[34:35] op_sel:[1,0,0]
	v_add_f32_dpp v130, v130, v130 row_mirror row_mask:0xf bank_mask:0xf bound_ctrl:1
	v_add_f32_dpp v131, v131, v131 row_mirror row_mask:0xf bank_mask:0xf bound_ctrl:1
	v_pk_fma_f32 v[92:93], v[116:117], v[130:131], v[92:93] op_sel_hi:[0,1,1]
	v_pk_fma_f32 v[94:95], v[116:117], v[130:131], v[94:95] op_sel:[1,0,0]
	v_pk_fma_f32 v[32:33], v[118:119], v[130:131], v[32:33] op_sel_hi:[0,1,1]
	v_pk_fma_f32 v[34:35], v[118:119], v[130:131], v[34:35] op_sel:[1,0,0]
	v_pk_mul_f32 v[12:13], v[92:93], v[124:125] op_sel_hi:[1,0]
	v_pk_fma_f32 v[12:13], v[94:95], v[124:125], v[12:13] op_sel:[0,1,0]
	v_pk_fma_f32 v[12:13], v[32:33], v[126:127], v[12:13] op_sel_hi:[1,0,1]
	v_pk_fma_f32 v[12:13], v[34:35], v[126:127], v[12:13] op_sel:[0,1,0]
	v_cvt_pk_f16_f32 v12, v12, v13
	ds_write2st64_b32 v47, v14, v12 offset0:56 offset1:60
	v_swap_b32 v93, v94
	v_swap_b32 v33, v34
	ds_read_b128 v[12:15], v114 offset:7936
	s_add_i32 s93, s93, 3
	s_and_b64 vcc, exec, s[82:83]
	s_cbranch_vccz .LBB0_409
	s_waitcnt lgkmcnt(3)
	v_cvt_f32_f16_sdwa v29, v50 dst_sel:DWORD dst_unused:UNUSED_PAD src0_sel:WORD_1
	v_cvt_f32_f16_e32 v28, v50
	v_cvt_f32_f16_sdwa v31, v51 dst_sel:DWORD dst_unused:UNUSED_PAD src0_sel:WORD_1
	v_cvt_f32_f16_e32 v30, v51
	s_waitcnt lgkmcnt(2)
	v_cvt_f32_f16_sdwa v17, v56 dst_sel:DWORD dst_unused:UNUSED_PAD src0_sel:WORD_1
	v_cvt_f32_f16_e32 v16, v56
	v_cvt_f32_f16_sdwa v19, v57 dst_sel:DWORD dst_unused:UNUSED_PAD src0_sel:WORD_1
	v_cvt_f32_f16_e32 v18, v57
	v_pk_mul_f32 v[22:23], v[0:1], v[28:29]
	v_pk_mul_f32 v[20:21], v[2:3], v[30:31]
	s_waitcnt lgkmcnt(2)
	v_pk_mul_f32 v[96:97], v[22:23], v[22:23]
	v_pk_mul_f32 v[90:91], v[20:21], v[20:21]
	v_add_f32_e32 v42, v96, v97
	v_cvt_f32_f16_sdwa v25, v48 dst_sel:DWORD dst_unused:UNUSED_PAD src0_sel:WORD_1
	v_cvt_f32_f16_e32 v24, v48
	v_cvt_f32_f16_sdwa v27, v49 dst_sel:DWORD dst_unused:UNUSED_PAD src0_sel:WORD_1
	v_cvt_f32_f16_e32 v26, v49
	v_add_f32_e32 v42, v90, v42
	v_add_f32_e32 v42, v91, v42
	v_pk_add_f32 v[90:91], v[16:17], -1.0 op_sel_hi:[1,0]
	v_pk_add_f32 v[96:97], v[18:19], -1.0 op_sel_hi:[1,0]
	v_pk_fma_f32 v[90:91], v[4:5], v[90:91], 1.0 op_sel_hi:[1,1,0]
	v_pk_fma_f32 v[96:97], v[6:7], v[96:97], 1.0 op_sel_hi:[1,1,0]
	v_pk_mul_f32 v[90:91], v[28:29], v[90:91]
	v_pk_mul_f32 v[96:97], v[30:31], v[96:97]
	v_pk_mul_f32 v[28:29], v[24:25], v[90:91]
	v_pk_mul_f32 v[30:31], v[26:27], v[96:97]
	v_pk_mul_f32 v[28:29], v[8:9], v[28:29]
	v_pk_mul_f32 v[30:31], v[10:11], v[30:31]
	v_add_f32_e32 v28, v28, v29
	v_add_f32_e32 v29, v30, v31
	v_add_f32_e32 v28, v28, v29
	v_add_f32_dpp v42, v42, v42 quad_perm:[1,0,3,2] row_mask:0xf bank_mask:0xf bound_ctrl:1
	s_nop 0
	v_add_f32_dpp v28, v28, v28 quad_perm:[1,0,3,2] row_mask:0xf bank_mask:0xf bound_ctrl:1
	v_add_f32_dpp v42, v42, v42 quad_perm:[2,3,0,1] row_mask:0xf bank_mask:0xf bound_ctrl:1
	s_nop 0
	v_add_f32_dpp v28, v28, v28 quad_perm:[2,3,0,1] row_mask:0xf bank_mask:0xf bound_ctrl:1
	v_add_f32_dpp v42, v42, v42 row_half_mirror row_mask:0xf bank_mask:0xf bound_ctrl:1
	s_nop 0
	v_add_f32_dpp v28, v28, v28 row_half_mirror row_mask:0xf bank_mask:0xf bound_ctrl:1
	v_mov_b32_dpp v47, v42 row_mirror row_mask:0xf bank_mask:0xf bound_ctrl:1
	s_nop 0
	v_mov_b32_dpp v29, v28 row_mirror row_mask:0xf bank_mask:0xf bound_ctrl:1
	s_and_saveexec_b64 s[12:13], s[6:7]
	s_cbranch_execz .LBB0_442
	s_add_i32 s94, s94, 48
	v_cmp_lt_u32_e32 vcc, s94, v106
	s_and_b64 exec, exec, vcc
	s_cbranch_execz .LBB0_442
	v_add_f32_e32 v30, v28, v29
	v_add_u32_e32 v28, s94, v46
	v_ashrrev_i32_e32 v29, 31, v28
	v_lshlrev_b64 v[28:29], 6, v[28:29]
	v_lshl_add_u64 v[28:29], s[58:59], 0, v[28:29]
	global_store_dword v[28:29], v30, off
